# combo on the transposed-reduce scan: S halves swapped in the dot products, staging waits count the trailing y store (vmcnt 1), no priority flips in the gemm0a and gemm1 k-loops
# speedup vs baseline: 1.0020x; 1.0020x over previous
.LBB0_63:
	s_or_b64 exec, exec, s[20:21]
	s_movk_i32 s0, 0x550
	v_lshrrev_b32_e32 v2, 2, v160
	v_lshrrev_b32_e32 v1, 4, v160
	v_mul_lo_u32 v91, v160, s0
	v_mul_lo_u32 v92, v2, s0
	s_lshl_b64 s[0:1], s[40:41], 20
	s_lshl_b32 s2, s89, 6
	v_bfi_b32 v0, 3, v1, v0
	v_and_b32_e32 v1, 15, v160
	s_or_b32 s20, s0, s2
	v_lshlrev_b32_e32 v93, 2, v1
	v_cmp_eq_u32_e64 s[30:31], 0, v1
	v_cmp_eq_u32_e64 s[70:71], 1, v1
	v_cmp_eq_u32_e64 s[72:73], 2, v1
	v_cmp_eq_u32_e64 s[74:75], 3, v1
	v_cmp_eq_u32_e64 s[82:83], 4, v1
	v_cmp_eq_u32_e64 s[48:49], 5, v1
	v_cmp_eq_u32_e64 s[38:39], 6, v1
	v_cmp_eq_u32_e64 s[42:43], 7, v1
	v_cmp_eq_u32_e64 s[44:45], 8, v1
	v_cmp_eq_u32_e32 vcc, 9, v1
	v_cmp_eq_u32_e64 s[58:59], 10, v1
	v_cmp_eq_u32_e64 s[60:61], 11, v1
	v_cmp_eq_u32_e64 s[62:63], 12, v1
	v_cmp_eq_u32_e64 s[64:65], 14, v1
	v_cmp_eq_u32_e64 s[66:67], 13, v1
	v_cmp_eq_u32_e64 s[68:69], 15, v1
	v_lshl_or_b32 v38, v1, 8, s20
	v_mov_b32_e32 v39, s1
	v_ashrrev_i32_e32 v1, 31, v0
	v_readlane_b32 s2, v254, 32
	v_lshl_add_u64 v[40:41], v[0:1], 2, v[38:39]
	v_readlane_b32 s3, v254, 33
	v_readlane_b32 s21, v254, 34
	v_add_u32_e32 v2, 0xffffff80, v160
	v_lshl_add_u64 v[68:69], s[2:3], 0, v[40:41]
	s_lshl_b64 s[2:3], s[40:41], 16
	s_add_u32 s2, s21, s2
	v_readlane_b32 s21, v254, 35
	s_addc_u32 s3, s21, s3
	v_lshl_add_u64 v[70:71], v[2:3], 4, s[2:3]
	s_lshl_b64 s[2:3], s[40:41], 19
	v_and_b32_e32 v1, 0x7f, v160
	v_lshl_or_b32 v40, v1, 4, s2
	v_mov_b32_e32 v41, s3
	v_lshl_add_u64 v[24:25], v[24:25], 0, v[40:41]
	s_mov_b64 s[2:3], 0x2b000
	v_lshl_add_u64 v[72:73], v[24:25], 0, s[2:3]
	v_lshl_add_u64 v[24:25], v[26:27], 0, v[40:41]
	v_lshl_add_u64 v[74:75], v[24:25], 0, s[2:3]
	v_readlane_b32 s2, v254, 36
	v_lshlrev_b32_e32 v35, 4, v160
	s_add_u32 s0, s2, s0
	v_readlane_b32 s2, v254, 37
	v_and_b32_e32 v36, 0xffffffc0, v35
	s_addc_u32 s1, s2, s1
	v_and_b32_e32 v1, 3, v160
	v_ashrrev_i32_e32 v37, 31, v36
	v_lshl_add_u64 v[76:77], v[32:33], 2, s[0:1]
	v_lshl_or_b32 v38, v1, 4, s20
	v_readlane_b32 s0, v254, 38
	v_lshl_add_u64 v[24:25], v[36:37], 2, v[38:39]
	v_readlane_b32 s1, v254, 39
	s_movk_i32 s24, 0x55
	v_lshlrev_b32_e32 v1, 2, v34
	v_lshl_add_u64 v[78:79], s[0:1], 0, v[24:25]
	s_mov_b64 s[0:1], 0
	s_waitcnt lgkmcnt(0)
	s_barrier
	s_waitcnt vmcnt(0)
	s_branch .LBB0_66

.LBB0_65:
	s_bitcmp1_b32 s40, 0
	s_cselect_b32 s2, 0x5500, 0
	v_lshl_or_b32 v94, v93, 2, s2
	v_lshl_add_u32 v95, v0, 2, s2
	v_mov_b32_e32 v96, s2
	v_mul_u32_u24_e32 v46, 0x154, v93
	v_add_u32_e32 v47, v46, v96
	v_add_u32_e32 v46, v46, v95
	ds_read_b64 v[44:45], v47 offset:1344
	ds_read_b32 v48, v46 offset:1280
	ds_read_b128 v[110:113], v94
	ds_read_b128 v[126:129], v94 offset:1024
	ds_read_b128 v[114:117], v94 offset:256
	ds_read_b128 v[118:121], v94 offset:512
	ds_read_b128 v[122:125], v94 offset:768
	ds_read_b32 v130, v95 offset:1280
	s_mov_b64 s[2:3], 0x100
	s_mov_b64 s[20:21], 0x800
	s_waitcnt lgkmcnt(4)
	v_pk_mul_f32 v[24:25], v[28:29], v[110:111]
	v_pk_mul_f32 v[26:27], v[28:29], v[126:127]
	v_pk_fma_f32 v[24:25], v[30:31], v[112:113], v[24:25]
	v_pk_fma_f32 v[26:27], v[30:31], v[128:129], v[26:27]
	v_add_f32_e32 v34, v24, v25
	ds_read_b128 v[134:137], v94 offset:1360
	v_add_f32_e32 v50, v26, v27
	v_add_f32_dpp v34, v34, v34 quad_perm:[1,0,3,2] row_mask:0xf bank_mask:0xf bound_ctrl:1
	ds_read_b128 v[150:153], v94 offset:2384
	ds_read_b128 v[138:141], v94 offset:1616
	v_add_f32_dpp v34, v34, v34 quad_perm:[2,3,0,1] row_mask:0xf bank_mask:0xf bound_ctrl:1
	s_waitcnt lgkmcnt(3)
	v_pk_mul_f32 v[36:37], v[122:123], v[130:131] op_sel_hi:[1,0]
	v_pk_mul_f32 v[38:39], v[124:125], v[130:131] op_sel_hi:[1,0]
	v_add_f32_dpp v34, v34, v34 row_ror:4 row_mask:0xf bank_mask:0xf bound_ctrl:1
	v_pk_fma_f32 v[36:37], v[28:29], v[118:119], v[36:37]
	v_pk_fma_f32 v[38:39], v[30:31], v[120:121], v[38:39]
	v_add_f32_dpp v34, v34, v34 row_ror:8 row_mask:0xf bank_mask:0xf bound_ctrl:1
	ds_read_b128 v[142:145], v94 offset:1872
	ds_read_b128 v[146:149], v94 offset:2128
	v_pk_fma_f32 v[28:29], v[114:115], v[34:35], v[36:37] op_sel_hi:[1,0,1] neg_lo:[0,1,0] neg_hi:[0,1,0]
	v_pk_fma_f32 v[30:31], v[116:117], v[34:35], v[38:39] op_sel_hi:[1,0,1] neg_lo:[0,1,0] neg_hi:[0,1,0]
	v_cndmask_b32_e64 v42, 0, v34, s[30:31]
	ds_read_b32 v154, v95 offset:2640
	s_waitcnt lgkmcnt(4)
	v_pk_mul_f32 v[24:25], v[28:29], v[134:135]
	v_pk_mul_f32 v[26:27], v[28:29], v[150:151]
	v_pk_fma_f32 v[24:25], v[30:31], v[136:137], v[24:25]
	v_pk_fma_f32 v[26:27], v[30:31], v[152:153], v[26:27]
	v_add_f32_e32 v34, v24, v25
	ds_read_b128 v[110:113], v94 offset:2720
	v_add_f32_e32 v51, v26, v27
	v_add_f32_dpp v34, v34, v34 quad_perm:[1,0,3,2] row_mask:0xf bank_mask:0xf bound_ctrl:1
	ds_read_b128 v[126:129], v94 offset:3744
	ds_read_b128 v[114:117], v94 offset:2976
	v_add_f32_dpp v34, v34, v34 quad_perm:[2,3,0,1] row_mask:0xf bank_mask:0xf bound_ctrl:1
	s_waitcnt lgkmcnt(3)
	v_pk_mul_f32 v[36:37], v[146:147], v[154:155] op_sel_hi:[1,0]
	v_pk_mul_f32 v[38:39], v[148:149], v[154:155] op_sel_hi:[1,0]
	v_add_f32_dpp v34, v34, v34 row_ror:4 row_mask:0xf bank_mask:0xf bound_ctrl:1
	v_pk_fma_f32 v[36:37], v[28:29], v[142:143], v[36:37]
	v_pk_fma_f32 v[38:39], v[30:31], v[144:145], v[38:39]
	v_add_f32_dpp v34, v34, v34 row_ror:8 row_mask:0xf bank_mask:0xf bound_ctrl:1
	ds_read_b128 v[118:121], v94 offset:3232
	ds_read_b128 v[122:125], v94 offset:3488
	v_pk_fma_f32 v[28:29], v[138:139], v[34:35], v[36:37] op_sel_hi:[1,0,1] neg_lo:[0,1,0] neg_hi:[0,1,0]
	v_pk_fma_f32 v[30:31], v[140:141], v[34:35], v[38:39] op_sel_hi:[1,0,1] neg_lo:[0,1,0] neg_hi:[0,1,0]
	v_cndmask_b32_e64 v42, v42, v34, s[70:71]
	ds_read_b32 v130, v95 offset:4000
	s_waitcnt lgkmcnt(4)
	v_pk_mul_f32 v[24:25], v[28:29], v[110:111]
	v_pk_mul_f32 v[26:27], v[28:29], v[126:127]
	v_pk_fma_f32 v[24:25], v[30:31], v[112:113], v[24:25]
	v_pk_fma_f32 v[26:27], v[30:31], v[128:129], v[26:27]
	v_add_f32_e32 v34, v24, v25
	ds_read_b128 v[134:137], v94 offset:4080
	v_add_f32_e32 v52, v26, v27
	v_add_f32_dpp v34, v34, v34 quad_perm:[1,0,3,2] row_mask:0xf bank_mask:0xf bound_ctrl:1
	ds_read_b128 v[150:153], v94 offset:5104
	ds_read_b128 v[138:141], v94 offset:4336
	v_add_f32_dpp v34, v34, v34 quad_perm:[2,3,0,1] row_mask:0xf bank_mask:0xf bound_ctrl:1
	s_waitcnt lgkmcnt(3)
	v_pk_mul_f32 v[36:37], v[122:123], v[130:131] op_sel_hi:[1,0]
	v_pk_mul_f32 v[38:39], v[124:125], v[130:131] op_sel_hi:[1,0]
	v_add_f32_dpp v34, v34, v34 row_ror:4 row_mask:0xf bank_mask:0xf bound_ctrl:1
	v_pk_fma_f32 v[36:37], v[28:29], v[118:119], v[36:37]
	v_pk_fma_f32 v[38:39], v[30:31], v[120:121], v[38:39]
	v_add_f32_dpp v34, v34, v34 row_ror:8 row_mask:0xf bank_mask:0xf bound_ctrl:1
	ds_read_b128 v[142:145], v94 offset:4592
	ds_read_b128 v[146:149], v94 offset:4848
	v_pk_fma_f32 v[28:29], v[114:115], v[34:35], v[36:37] op_sel_hi:[1,0,1] neg_lo:[0,1,0] neg_hi:[0,1,0]
	v_pk_fma_f32 v[30:31], v[116:117], v[34:35], v[38:39] op_sel_hi:[1,0,1] neg_lo:[0,1,0] neg_hi:[0,1,0]
	v_cndmask_b32_e64 v42, v42, v34, s[72:73]
	ds_read_b32 v154, v95 offset:5360
	s_waitcnt lgkmcnt(4)
	v_pk_mul_f32 v[24:25], v[28:29], v[134:135]
	v_pk_mul_f32 v[26:27], v[28:29], v[150:151]
	v_pk_fma_f32 v[24:25], v[30:31], v[136:137], v[24:25]
	v_pk_fma_f32 v[26:27], v[30:31], v[152:153], v[26:27]
	v_add_f32_e32 v34, v24, v25
	ds_read_b128 v[110:113], v94 offset:5440
	v_add_f32_e32 v53, v26, v27
	v_add_f32_dpp v34, v34, v34 quad_perm:[1,0,3,2] row_mask:0xf bank_mask:0xf bound_ctrl:1
	ds_read_b128 v[126:129], v94 offset:6464
	ds_read_b128 v[114:117], v94 offset:5696
	v_add_f32_dpp v34, v34, v34 quad_perm:[2,3,0,1] row_mask:0xf bank_mask:0xf bound_ctrl:1
	s_waitcnt lgkmcnt(3)
	v_pk_mul_f32 v[36:37], v[146:147], v[154:155] op_sel_hi:[1,0]
	v_pk_mul_f32 v[38:39], v[148:149], v[154:155] op_sel_hi:[1,0]
	v_add_f32_dpp v34, v34, v34 row_ror:4 row_mask:0xf bank_mask:0xf bound_ctrl:1
	v_pk_fma_f32 v[36:37], v[28:29], v[142:143], v[36:37]
	v_pk_fma_f32 v[38:39], v[30:31], v[144:145], v[38:39]
	v_add_f32_dpp v34, v34, v34 row_ror:8 row_mask:0xf bank_mask:0xf bound_ctrl:1
	ds_read_b128 v[118:121], v94 offset:5952
	ds_read_b128 v[122:125], v94 offset:6208
	v_pk_fma_f32 v[28:29], v[138:139], v[34:35], v[36:37] op_sel_hi:[1,0,1] neg_lo:[0,1,0] neg_hi:[0,1,0]
	v_pk_fma_f32 v[30:31], v[140:141], v[34:35], v[38:39] op_sel_hi:[1,0,1] neg_lo:[0,1,0] neg_hi:[0,1,0]
	v_cndmask_b32_e64 v42, v42, v34, s[74:75]
	ds_read_b32 v130, v95 offset:6720
	s_waitcnt lgkmcnt(4)
	v_pk_mul_f32 v[24:25], v[28:29], v[110:111]
	v_pk_mul_f32 v[26:27], v[28:29], v[126:127]
	v_pk_fma_f32 v[24:25], v[30:31], v[112:113], v[24:25]
	v_pk_fma_f32 v[26:27], v[30:31], v[128:129], v[26:27]
	v_add_f32_e32 v34, v24, v25
	ds_read_b128 v[134:137], v94 offset:6800
	v_add_f32_e32 v54, v26, v27
	v_add_f32_dpp v34, v34, v34 quad_perm:[1,0,3,2] row_mask:0xf bank_mask:0xf bound_ctrl:1
	ds_read_b128 v[150:153], v94 offset:7824
	ds_read_b128 v[138:141], v94 offset:7056
	v_add_f32_dpp v34, v34, v34 quad_perm:[2,3,0,1] row_mask:0xf bank_mask:0xf bound_ctrl:1
	s_waitcnt lgkmcnt(3)
	v_pk_mul_f32 v[36:37], v[122:123], v[130:131] op_sel_hi:[1,0]
	v_pk_mul_f32 v[38:39], v[124:125], v[130:131] op_sel_hi:[1,0]
	v_add_f32_dpp v34, v34, v34 row_ror:4 row_mask:0xf bank_mask:0xf bound_ctrl:1
	v_pk_fma_f32 v[36:37], v[28:29], v[118:119], v[36:37]
	v_pk_fma_f32 v[38:39], v[30:31], v[120:121], v[38:39]
	v_add_f32_dpp v34, v34, v34 row_ror:8 row_mask:0xf bank_mask:0xf bound_ctrl:1
	ds_read_b128 v[142:145], v94 offset:7312
	ds_read_b128 v[146:149], v94 offset:7568
	v_pk_fma_f32 v[28:29], v[114:115], v[34:35], v[36:37] op_sel_hi:[1,0,1] neg_lo:[0,1,0] neg_hi:[0,1,0]
	v_pk_fma_f32 v[30:31], v[116:117], v[34:35], v[38:39] op_sel_hi:[1,0,1] neg_lo:[0,1,0] neg_hi:[0,1,0]
	v_cndmask_b32_e64 v42, v42, v34, s[82:83]
	ds_read_b32 v154, v95 offset:8080
	s_waitcnt lgkmcnt(4)
	v_pk_mul_f32 v[24:25], v[28:29], v[134:135]
	v_pk_mul_f32 v[26:27], v[28:29], v[150:151]
	v_pk_fma_f32 v[24:25], v[30:31], v[136:137], v[24:25]
	v_pk_fma_f32 v[26:27], v[30:31], v[152:153], v[26:27]
	v_add_f32_e32 v34, v24, v25
	ds_read_b128 v[110:113], v94 offset:8160
	v_add_f32_e32 v55, v26, v27
	v_add_f32_dpp v34, v34, v34 quad_perm:[1,0,3,2] row_mask:0xf bank_mask:0xf bound_ctrl:1
	ds_read_b128 v[126:129], v94 offset:9184
	ds_read_b128 v[114:117], v94 offset:8416
	v_add_f32_dpp v34, v34, v34 quad_perm:[2,3,0,1] row_mask:0xf bank_mask:0xf bound_ctrl:1
	s_waitcnt lgkmcnt(3)
	v_pk_mul_f32 v[36:37], v[146:147], v[154:155] op_sel_hi:[1,0]
	v_pk_mul_f32 v[38:39], v[148:149], v[154:155] op_sel_hi:[1,0]
	v_add_f32_dpp v34, v34, v34 row_ror:4 row_mask:0xf bank_mask:0xf bound_ctrl:1
	v_pk_fma_f32 v[36:37], v[28:29], v[142:143], v[36:37]
	v_pk_fma_f32 v[38:39], v[30:31], v[144:145], v[38:39]
	v_add_f32_dpp v34, v34, v34 row_ror:8 row_mask:0xf bank_mask:0xf bound_ctrl:1
	ds_read_b128 v[118:121], v94 offset:8672
	ds_read_b128 v[122:125], v94 offset:8928
	v_pk_fma_f32 v[28:29], v[138:139], v[34:35], v[36:37] op_sel_hi:[1,0,1] neg_lo:[0,1,0] neg_hi:[0,1,0]
	v_pk_fma_f32 v[30:31], v[140:141], v[34:35], v[38:39] op_sel_hi:[1,0,1] neg_lo:[0,1,0] neg_hi:[0,1,0]
	v_cndmask_b32_e64 v42, v42, v34, s[48:49]
	ds_read_b32 v130, v95 offset:9440
	s_waitcnt lgkmcnt(4)
	v_pk_mul_f32 v[24:25], v[28:29], v[110:111]
	v_pk_mul_f32 v[26:27], v[28:29], v[126:127]
	v_pk_fma_f32 v[24:25], v[30:31], v[112:113], v[24:25]
	v_pk_fma_f32 v[26:27], v[30:31], v[128:129], v[26:27]
	v_add_f32_e32 v34, v24, v25
	ds_read_b128 v[134:137], v94 offset:9520
	v_add_f32_e32 v56, v26, v27
	v_add_f32_dpp v34, v34, v34 quad_perm:[1,0,3,2] row_mask:0xf bank_mask:0xf bound_ctrl:1
	ds_read_b128 v[150:153], v94 offset:10544
	ds_read_b128 v[138:141], v94 offset:9776
	v_add_f32_dpp v34, v34, v34 quad_perm:[2,3,0,1] row_mask:0xf bank_mask:0xf bound_ctrl:1
	s_waitcnt lgkmcnt(3)
	v_pk_mul_f32 v[36:37], v[122:123], v[130:131] op_sel_hi:[1,0]
	v_pk_mul_f32 v[38:39], v[124:125], v[130:131] op_sel_hi:[1,0]
	v_add_f32_dpp v34, v34, v34 row_ror:4 row_mask:0xf bank_mask:0xf bound_ctrl:1
	v_pk_fma_f32 v[36:37], v[28:29], v[118:119], v[36:37]
	v_pk_fma_f32 v[38:39], v[30:31], v[120:121], v[38:39]
	v_add_f32_dpp v34, v34, v34 row_ror:8 row_mask:0xf bank_mask:0xf bound_ctrl:1
	ds_read_b128 v[142:145], v94 offset:10032
	ds_read_b128 v[146:149], v94 offset:10288
	v_pk_fma_f32 v[28:29], v[114:115], v[34:35], v[36:37] op_sel_hi:[1,0,1] neg_lo:[0,1,0] neg_hi:[0,1,0]
	v_pk_fma_f32 v[30:31], v[116:117], v[34:35], v[38:39] op_sel_hi:[1,0,1] neg_lo:[0,1,0] neg_hi:[0,1,0]
	v_cndmask_b32_e64 v42, v42, v34, s[38:39]
	ds_read_b32 v154, v95 offset:10800
	s_waitcnt lgkmcnt(4)
	v_pk_mul_f32 v[24:25], v[28:29], v[134:135]
	v_pk_mul_f32 v[26:27], v[28:29], v[150:151]
	v_pk_fma_f32 v[24:25], v[30:31], v[136:137], v[24:25]
	v_pk_fma_f32 v[26:27], v[30:31], v[152:153], v[26:27]
	v_add_f32_e32 v34, v24, v25
	ds_read_b128 v[110:113], v94 offset:10880
	v_add_f32_e32 v57, v26, v27
	v_add_f32_dpp v34, v34, v34 quad_perm:[1,0,3,2] row_mask:0xf bank_mask:0xf bound_ctrl:1
	ds_read_b128 v[126:129], v94 offset:11904
	ds_read_b128 v[114:117], v94 offset:11136
	v_add_f32_dpp v34, v34, v34 quad_perm:[2,3,0,1] row_mask:0xf bank_mask:0xf bound_ctrl:1
	s_waitcnt lgkmcnt(3)
	v_pk_mul_f32 v[36:37], v[146:147], v[154:155] op_sel_hi:[1,0]
	v_pk_mul_f32 v[38:39], v[148:149], v[154:155] op_sel_hi:[1,0]
	v_add_f32_dpp v34, v34, v34 row_ror:4 row_mask:0xf bank_mask:0xf bound_ctrl:1
	v_pk_fma_f32 v[36:37], v[28:29], v[142:143], v[36:37]
	v_pk_fma_f32 v[38:39], v[30:31], v[144:145], v[38:39]
	v_add_f32_dpp v34, v34, v34 row_ror:8 row_mask:0xf bank_mask:0xf bound_ctrl:1
	ds_read_b128 v[118:121], v94 offset:11392
	ds_read_b128 v[122:125], v94 offset:11648
	v_pk_fma_f32 v[28:29], v[138:139], v[34:35], v[36:37] op_sel_hi:[1,0,1] neg_lo:[0,1,0] neg_hi:[0,1,0]
	v_pk_fma_f32 v[30:31], v[140:141], v[34:35], v[38:39] op_sel_hi:[1,0,1] neg_lo:[0,1,0] neg_hi:[0,1,0]
	v_cndmask_b32_e64 v42, v42, v34, s[42:43]
	ds_read_b32 v130, v95 offset:12160
	s_waitcnt lgkmcnt(4)
	v_pk_mul_f32 v[24:25], v[28:29], v[110:111]
	v_pk_mul_f32 v[26:27], v[28:29], v[126:127]
	v_pk_fma_f32 v[24:25], v[30:31], v[112:113], v[24:25]
	v_pk_fma_f32 v[26:27], v[30:31], v[128:129], v[26:27]
	v_add_f32_e32 v34, v24, v25
	ds_read_b128 v[134:137], v94 offset:12240
	v_add_f32_e32 v58, v26, v27
	v_add_f32_dpp v34, v34, v34 quad_perm:[1,0,3,2] row_mask:0xf bank_mask:0xf bound_ctrl:1
	ds_read_b128 v[150:153], v94 offset:13264
	ds_read_b128 v[138:141], v94 offset:12496
	v_add_f32_dpp v34, v34, v34 quad_perm:[2,3,0,1] row_mask:0xf bank_mask:0xf bound_ctrl:1
	s_waitcnt lgkmcnt(3)
	v_pk_mul_f32 v[36:37], v[122:123], v[130:131] op_sel_hi:[1,0]
	v_pk_mul_f32 v[38:39], v[124:125], v[130:131] op_sel_hi:[1,0]
	v_add_f32_dpp v34, v34, v34 row_ror:4 row_mask:0xf bank_mask:0xf bound_ctrl:1
	v_pk_fma_f32 v[36:37], v[28:29], v[118:119], v[36:37]
	v_pk_fma_f32 v[38:39], v[30:31], v[120:121], v[38:39]
	v_add_f32_dpp v34, v34, v34 row_ror:8 row_mask:0xf bank_mask:0xf bound_ctrl:1
	ds_read_b128 v[142:145], v94 offset:12752
	ds_read_b128 v[146:149], v94 offset:13008
	v_pk_fma_f32 v[28:29], v[114:115], v[34:35], v[36:37] op_sel_hi:[1,0,1] neg_lo:[0,1,0] neg_hi:[0,1,0]
	v_pk_fma_f32 v[30:31], v[116:117], v[34:35], v[38:39] op_sel_hi:[1,0,1] neg_lo:[0,1,0] neg_hi:[0,1,0]
	v_cndmask_b32_e64 v42, v42, v34, s[44:45]
	ds_read_b32 v154, v95 offset:13520
	s_waitcnt lgkmcnt(4)
	v_pk_mul_f32 v[24:25], v[28:29], v[134:135]
	v_pk_mul_f32 v[26:27], v[28:29], v[150:151]
	v_pk_fma_f32 v[24:25], v[30:31], v[136:137], v[24:25]
	v_pk_fma_f32 v[26:27], v[30:31], v[152:153], v[26:27]
	v_add_f32_e32 v34, v24, v25
	ds_read_b128 v[110:113], v94 offset:13600
	v_add_f32_e32 v59, v26, v27
	v_add_f32_dpp v34, v34, v34 quad_perm:[1,0,3,2] row_mask:0xf bank_mask:0xf bound_ctrl:1
	ds_read_b128 v[126:129], v94 offset:14624
	ds_read_b128 v[114:117], v94 offset:13856
	v_add_f32_dpp v34, v34, v34 quad_perm:[2,3,0,1] row_mask:0xf bank_mask:0xf bound_ctrl:1
	s_waitcnt lgkmcnt(3)
	v_pk_mul_f32 v[36:37], v[146:147], v[154:155] op_sel_hi:[1,0]
	v_pk_mul_f32 v[38:39], v[148:149], v[154:155] op_sel_hi:[1,0]
	v_add_f32_dpp v34, v34, v34 row_ror:4 row_mask:0xf bank_mask:0xf bound_ctrl:1
	v_pk_fma_f32 v[36:37], v[28:29], v[142:143], v[36:37]
	v_pk_fma_f32 v[38:39], v[30:31], v[144:145], v[38:39]
	v_add_f32_dpp v34, v34, v34 row_ror:8 row_mask:0xf bank_mask:0xf bound_ctrl:1
	ds_read_b128 v[118:121], v94 offset:14112
	ds_read_b128 v[122:125], v94 offset:14368
	v_pk_fma_f32 v[28:29], v[138:139], v[34:35], v[36:37] op_sel_hi:[1,0,1] neg_lo:[0,1,0] neg_hi:[0,1,0]
	v_pk_fma_f32 v[30:31], v[140:141], v[34:35], v[38:39] op_sel_hi:[1,0,1] neg_lo:[0,1,0] neg_hi:[0,1,0]
	v_cndmask_b32_e32 v42, v42, v34, vcc
	ds_read_b32 v130, v95 offset:14880
	s_waitcnt lgkmcnt(4)
	v_pk_mul_f32 v[24:25], v[28:29], v[110:111]
	v_pk_mul_f32 v[26:27], v[28:29], v[126:127]
	v_pk_fma_f32 v[24:25], v[30:31], v[112:113], v[24:25]
	v_pk_fma_f32 v[26:27], v[30:31], v[128:129], v[26:27]
	v_add_f32_e32 v34, v24, v25
	ds_read_b128 v[134:137], v94 offset:14960
	v_add_f32_e32 v60, v26, v27
	v_add_f32_dpp v34, v34, v34 quad_perm:[1,0,3,2] row_mask:0xf bank_mask:0xf bound_ctrl:1
	ds_read_b128 v[150:153], v94 offset:15984
	ds_read_b128 v[138:141], v94 offset:15216
	v_add_f32_dpp v34, v34, v34 quad_perm:[2,3,0,1] row_mask:0xf bank_mask:0xf bound_ctrl:1
	s_waitcnt lgkmcnt(3)
	v_pk_mul_f32 v[36:37], v[122:123], v[130:131] op_sel_hi:[1,0]
	v_pk_mul_f32 v[38:39], v[124:125], v[130:131] op_sel_hi:[1,0]
	v_add_f32_dpp v34, v34, v34 row_ror:4 row_mask:0xf bank_mask:0xf bound_ctrl:1
	v_pk_fma_f32 v[36:37], v[28:29], v[118:119], v[36:37]
	v_pk_fma_f32 v[38:39], v[30:31], v[120:121], v[38:39]
	v_add_f32_dpp v34, v34, v34 row_ror:8 row_mask:0xf bank_mask:0xf bound_ctrl:1
	ds_read_b128 v[142:145], v94 offset:15472
	ds_read_b128 v[146:149], v94 offset:15728
	v_pk_fma_f32 v[28:29], v[114:115], v[34:35], v[36:37] op_sel_hi:[1,0,1] neg_lo:[0,1,0] neg_hi:[0,1,0]
	v_pk_fma_f32 v[30:31], v[116:117], v[34:35], v[38:39] op_sel_hi:[1,0,1] neg_lo:[0,1,0] neg_hi:[0,1,0]
	v_cndmask_b32_e64 v42, v42, v34, s[58:59]
	ds_read_b32 v154, v95 offset:16240
	s_waitcnt lgkmcnt(4)
	v_pk_mul_f32 v[24:25], v[28:29], v[134:135]
	v_pk_mul_f32 v[26:27], v[28:29], v[150:151]
	v_pk_fma_f32 v[24:25], v[30:31], v[136:137], v[24:25]
	v_pk_fma_f32 v[26:27], v[30:31], v[152:153], v[26:27]
	v_add_f32_e32 v34, v24, v25
	ds_read_b128 v[110:113], v94 offset:16320
	v_add_f32_e32 v61, v26, v27
	v_add_f32_dpp v34, v34, v34 quad_perm:[1,0,3,2] row_mask:0xf bank_mask:0xf bound_ctrl:1
	ds_read_b128 v[126:129], v94 offset:17344
	ds_read_b128 v[114:117], v94 offset:16576
	v_add_f32_dpp v34, v34, v34 quad_perm:[2,3,0,1] row_mask:0xf bank_mask:0xf bound_ctrl:1
	s_waitcnt lgkmcnt(3)
	v_pk_mul_f32 v[36:37], v[146:147], v[154:155] op_sel_hi:[1,0]
	v_pk_mul_f32 v[38:39], v[148:149], v[154:155] op_sel_hi:[1,0]
	v_add_f32_dpp v34, v34, v34 row_ror:4 row_mask:0xf bank_mask:0xf bound_ctrl:1
	v_pk_fma_f32 v[36:37], v[28:29], v[142:143], v[36:37]
	v_pk_fma_f32 v[38:39], v[30:31], v[144:145], v[38:39]
	v_add_f32_dpp v34, v34, v34 row_ror:8 row_mask:0xf bank_mask:0xf bound_ctrl:1
	ds_read_b128 v[118:121], v94 offset:16832
	ds_read_b128 v[122:125], v94 offset:17088
	v_pk_fma_f32 v[28:29], v[138:139], v[34:35], v[36:37] op_sel_hi:[1,0,1] neg_lo:[0,1,0] neg_hi:[0,1,0]
	v_pk_fma_f32 v[30:31], v[140:141], v[34:35], v[38:39] op_sel_hi:[1,0,1] neg_lo:[0,1,0] neg_hi:[0,1,0]
	v_cndmask_b32_e64 v42, v42, v34, s[60:61]
	ds_read_b32 v130, v95 offset:17600
	s_waitcnt lgkmcnt(4)
	v_pk_mul_f32 v[24:25], v[28:29], v[110:111]
	v_pk_mul_f32 v[26:27], v[28:29], v[126:127]
	v_pk_fma_f32 v[24:25], v[30:31], v[112:113], v[24:25]
	v_pk_fma_f32 v[26:27], v[30:31], v[128:129], v[26:27]
	v_add_f32_e32 v34, v24, v25
	ds_read_b128 v[134:137], v94 offset:17680
	v_add_f32_e32 v62, v26, v27
	v_add_f32_dpp v34, v34, v34 quad_perm:[1,0,3,2] row_mask:0xf bank_mask:0xf bound_ctrl:1
	ds_read_b128 v[150:153], v94 offset:18704
	ds_read_b128 v[138:141], v94 offset:17936
	v_add_f32_dpp v34, v34, v34 quad_perm:[2,3,0,1] row_mask:0xf bank_mask:0xf bound_ctrl:1
	s_waitcnt lgkmcnt(3)
	v_pk_mul_f32 v[36:37], v[122:123], v[130:131] op_sel_hi:[1,0]
	v_pk_mul_f32 v[38:39], v[124:125], v[130:131] op_sel_hi:[1,0]
	v_add_f32_dpp v34, v34, v34 row_ror:4 row_mask:0xf bank_mask:0xf bound_ctrl:1
	v_pk_fma_f32 v[36:37], v[28:29], v[118:119], v[36:37]
	v_pk_fma_f32 v[38:39], v[30:31], v[120:121], v[38:39]
	v_add_f32_dpp v34, v34, v34 row_ror:8 row_mask:0xf bank_mask:0xf bound_ctrl:1
	ds_read_b128 v[142:145], v94 offset:18192
	ds_read_b128 v[146:149], v94 offset:18448
	v_pk_fma_f32 v[28:29], v[114:115], v[34:35], v[36:37] op_sel_hi:[1,0,1] neg_lo:[0,1,0] neg_hi:[0,1,0]
	v_pk_fma_f32 v[30:31], v[116:117], v[34:35], v[38:39] op_sel_hi:[1,0,1] neg_lo:[0,1,0] neg_hi:[0,1,0]
	v_cndmask_b32_e64 v42, v42, v34, s[62:63]
	ds_read_b32 v154, v95 offset:18960
	s_waitcnt lgkmcnt(4)
	v_pk_mul_f32 v[24:25], v[28:29], v[134:135]
	v_pk_mul_f32 v[26:27], v[28:29], v[150:151]
	v_pk_fma_f32 v[24:25], v[30:31], v[136:137], v[24:25]
	v_pk_fma_f32 v[26:27], v[30:31], v[152:153], v[26:27]
	v_add_f32_e32 v34, v24, v25
	ds_read_b128 v[110:113], v94 offset:19040
	v_add_f32_e32 v63, v26, v27
	v_add_f32_dpp v34, v34, v34 quad_perm:[1,0,3,2] row_mask:0xf bank_mask:0xf bound_ctrl:1
	ds_read_b128 v[126:129], v94 offset:20064
	ds_read_b128 v[114:117], v94 offset:19296
	v_add_f32_dpp v34, v34, v34 quad_perm:[2,3,0,1] row_mask:0xf bank_mask:0xf bound_ctrl:1
	s_waitcnt lgkmcnt(3)
	v_pk_mul_f32 v[36:37], v[146:147], v[154:155] op_sel_hi:[1,0]
	v_pk_mul_f32 v[38:39], v[148:149], v[154:155] op_sel_hi:[1,0]
	v_add_f32_dpp v34, v34, v34 row_ror:4 row_mask:0xf bank_mask:0xf bound_ctrl:1
	v_pk_fma_f32 v[36:37], v[28:29], v[142:143], v[36:37]
	v_pk_fma_f32 v[38:39], v[30:31], v[144:145], v[38:39]
	v_add_f32_dpp v34, v34, v34 row_ror:8 row_mask:0xf bank_mask:0xf bound_ctrl:1
	ds_read_b128 v[118:121], v94 offset:19552
	ds_read_b128 v[122:125], v94 offset:19808
	v_pk_fma_f32 v[28:29], v[138:139], v[34:35], v[36:37] op_sel_hi:[1,0,1] neg_lo:[0,1,0] neg_hi:[0,1,0]
	v_pk_fma_f32 v[30:31], v[140:141], v[34:35], v[38:39] op_sel_hi:[1,0,1] neg_lo:[0,1,0] neg_hi:[0,1,0]
	v_cndmask_b32_e64 v42, v42, v34, s[66:67]
	ds_read_b32 v130, v95 offset:20320
	s_waitcnt lgkmcnt(4)
	v_pk_mul_f32 v[24:25], v[28:29], v[110:111]
	v_pk_mul_f32 v[26:27], v[28:29], v[126:127]
	v_pk_fma_f32 v[24:25], v[30:31], v[112:113], v[24:25]
	v_pk_fma_f32 v[26:27], v[30:31], v[128:129], v[26:27]
	v_add_f32_e32 v34, v24, v25
	ds_read_b128 v[134:137], v94 offset:20400
	v_add_f32_e32 v64, v26, v27
	v_add_f32_dpp v34, v34, v34 quad_perm:[1,0,3,2] row_mask:0xf bank_mask:0xf bound_ctrl:1
	ds_read_b128 v[150:153], v94 offset:21424
	ds_read_b128 v[138:141], v94 offset:20656
	v_add_f32_dpp v34, v34, v34 quad_perm:[2,3,0,1] row_mask:0xf bank_mask:0xf bound_ctrl:1
	s_waitcnt lgkmcnt(3)
	v_pk_mul_f32 v[36:37], v[122:123], v[130:131] op_sel_hi:[1,0]
	v_pk_mul_f32 v[38:39], v[124:125], v[130:131] op_sel_hi:[1,0]
	v_add_f32_dpp v34, v34, v34 row_ror:4 row_mask:0xf bank_mask:0xf bound_ctrl:1
	v_pk_fma_f32 v[36:37], v[28:29], v[118:119], v[36:37]
	v_pk_fma_f32 v[38:39], v[30:31], v[120:121], v[38:39]
	v_add_f32_dpp v34, v34, v34 row_ror:8 row_mask:0xf bank_mask:0xf bound_ctrl:1
	ds_read_b128 v[142:145], v94 offset:20912
	ds_read_b128 v[146:149], v94 offset:21168
	v_pk_fma_f32 v[28:29], v[114:115], v[34:35], v[36:37] op_sel_hi:[1,0,1] neg_lo:[0,1,0] neg_hi:[0,1,0]
	v_pk_fma_f32 v[30:31], v[116:117], v[34:35], v[38:39] op_sel_hi:[1,0,1] neg_lo:[0,1,0] neg_hi:[0,1,0]
	v_cndmask_b32_e64 v42, v42, v34, s[64:65]
	ds_read_b32 v154, v95 offset:21680
	s_waitcnt lgkmcnt(4)
	v_pk_mul_f32 v[24:25], v[28:29], v[134:135]
	v_pk_mul_f32 v[26:27], v[28:29], v[150:151]
	v_pk_fma_f32 v[24:25], v[30:31], v[136:137], v[24:25]
	v_pk_fma_f32 v[26:27], v[30:31], v[152:153], v[26:27]
	v_add_f32_e32 v34, v24, v25
	v_lshl_add_u64 v[70:71], v[70:71], 0, s[2:3]
	v_add_f32_e32 v65, v26, v27
	v_add_f32_dpp v34, v34, v34 quad_perm:[1,0,3,2] row_mask:0xf bank_mask:0xf bound_ctrl:1
	v_lshl_add_u64 v[72:73], v[72:73], 0, s[20:21]
	v_lshl_add_u64 v[74:75], v[74:75], 0, s[20:21]
	v_add_f32_dpp v34, v34, v34 quad_perm:[2,3,0,1] row_mask:0xf bank_mask:0xf bound_ctrl:1
	s_waitcnt lgkmcnt(0)
	v_pk_mul_f32 v[36:37], v[146:147], v[154:155] op_sel_hi:[1,0]
	v_pk_mul_f32 v[38:39], v[148:149], v[154:155] op_sel_hi:[1,0]
	v_add_f32_dpp v34, v34, v34 row_ror:4 row_mask:0xf bank_mask:0xf bound_ctrl:1
	v_pk_fma_f32 v[36:37], v[28:29], v[142:143], v[36:37]
	v_pk_fma_f32 v[38:39], v[30:31], v[144:145], v[38:39]
	v_add_f32_dpp v34, v34, v34 row_ror:8 row_mask:0xf bank_mask:0xf bound_ctrl:1
	v_pk_fma_f32 v[28:29], v[138:139], v[34:35], v[36:37] op_sel_hi:[1,0,1] neg_lo:[0,1,0] neg_hi:[0,1,0]
	v_pk_fma_f32 v[30:31], v[140:141], v[34:35], v[38:39] op_sel_hi:[1,0,1] neg_lo:[0,1,0] neg_hi:[0,1,0]
	v_cndmask_b32_e64 v42, v42, v34, s[68:69]
	v_add_f32_dpp v50, v50, v50 row_ror:8 row_mask:0xf bank_mask:0xf bound_ctrl:1
	v_add_f32_dpp v51, v51, v51 row_ror:8 row_mask:0xf bank_mask:0xf bound_ctrl:1
	v_add_f32_dpp v52, v52, v52 row_ror:8 row_mask:0xf bank_mask:0xf bound_ctrl:1
	v_add_f32_dpp v53, v53, v53 row_ror:8 row_mask:0xf bank_mask:0xf bound_ctrl:1
	v_add_f32_dpp v54, v54, v54 row_ror:8 row_mask:0xf bank_mask:0xf bound_ctrl:1
	v_add_f32_dpp v55, v55, v55 row_ror:8 row_mask:0xf bank_mask:0xf bound_ctrl:1
	v_add_f32_dpp v56, v56, v56 row_ror:8 row_mask:0xf bank_mask:0xf bound_ctrl:1
	v_add_f32_dpp v57, v57, v57 row_ror:8 row_mask:0xf bank_mask:0xf bound_ctrl:1
	v_add_f32_dpp v50, v58, v58 row_ror:8 row_mask:0xf bank_mask:0xc bound_ctrl:1
	v_add_f32_dpp v51, v59, v59 row_ror:8 row_mask:0xf bank_mask:0xc bound_ctrl:1
	v_add_f32_dpp v52, v60, v60 row_ror:8 row_mask:0xf bank_mask:0xc bound_ctrl:1
	v_add_f32_dpp v53, v61, v61 row_ror:8 row_mask:0xf bank_mask:0xc bound_ctrl:1
	v_add_f32_dpp v54, v62, v62 row_ror:8 row_mask:0xf bank_mask:0xc bound_ctrl:1
	v_add_f32_dpp v55, v63, v63 row_ror:8 row_mask:0xf bank_mask:0xc bound_ctrl:1
	v_add_f32_dpp v56, v64, v64 row_ror:8 row_mask:0xf bank_mask:0xc bound_ctrl:1
	v_add_f32_dpp v57, v65, v65 row_ror:8 row_mask:0xf bank_mask:0xc bound_ctrl:1
	s_mov_b32 s2, 0xcccccccc
	s_mov_b32 s3, 0xcccccccc
	v_add_f32_dpp v50, v50, v50 row_half_mirror row_mask:0xf bank_mask:0x5 bound_ctrl:1
	v_add_f32_dpp v51, v51, v51 row_half_mirror row_mask:0xf bank_mask:0x5 bound_ctrl:1
	v_add_f32_dpp v52, v52, v52 row_half_mirror row_mask:0xf bank_mask:0x5 bound_ctrl:1
	v_add_f32_dpp v53, v53, v53 row_half_mirror row_mask:0xf bank_mask:0x5 bound_ctrl:1
	s_mov_b32 s20, 0xaaaaaaaa
	s_mov_b32 s21, 0xaaaaaaaa
	v_add_f32_dpp v50, v54, v54 row_half_mirror row_mask:0xf bank_mask:0xa bound_ctrl:1
	v_add_f32_dpp v51, v55, v55 row_half_mirror row_mask:0xf bank_mask:0xa bound_ctrl:1
	v_add_f32_dpp v52, v56, v56 row_half_mirror row_mask:0xf bank_mask:0xa bound_ctrl:1
	v_add_f32_dpp v53, v57, v57 row_half_mirror row_mask:0xf bank_mask:0xa bound_ctrl:1
	v_cndmask_b32_e64 v58, v52, v50, s[2:3]
	v_cndmask_b32_e64 v59, v53, v51, s[2:3]
	v_cndmask_b32_e64 v60, v50, v52, s[2:3]
	v_cndmask_b32_e64 v61, v51, v53, s[2:3]
	v_add_f32_dpp v50, v58, v60 quad_perm:[2,3,0,1] row_mask:0xf bank_mask:0xf bound_ctrl:1
	v_add_f32_dpp v51, v59, v61 quad_perm:[2,3,0,1] row_mask:0xf bank_mask:0xf bound_ctrl:1
	v_lshl_add_u64 v[24:25], v[68:69], 0, s[0:1]
	s_add_u32 s0, s0, 0x1000
	s_addc_u32 s1, s1, 0
	v_cndmask_b32_e64 v58, v51, v50, s[20:21]
	v_cndmask_b32_e64 v60, v50, v51, s[20:21]
	s_add_i32 s24, s24, 1
	s_cmp_lg_u32 s0, 0xac000
	v_add_f32_dpp v43, v58, v60 quad_perm:[1,0,3,2] row_mask:0xf bank_mask:0xf bound_ctrl:1
	v_fma_f32 v40, -v44, v42, v43
	v_fmac_f32_e32 v40, v48, v45
	global_store_dword v[24:25], v40, off
	s_barrier
	s_cbranch_scc0 .LBB0_81
.LBB0_66:
	s_add_i32 s40, s24, -1
	s_cmpk_gt_u32 s40, 0xfe
	s_cbranch_scc1 .LBB0_74
	s_bitcmp1_b32 s24, 0
	s_cselect_b32 s41, 0x5500, 0
	v_lshlrev_b32_e32 v2, 2, v85
	v_add3_u32 v2, s41, v2, v86
	v_lshl_add_u32 v32, v87, 2, v2
	s_waitcnt vmcnt(1)
	v_lshlrev_b32_e32 v24, 16, v12
	v_and_b32_e32 v25, 0xffff0000, v12
	v_lshlrev_b32_e32 v26, 16, v13
	v_and_b32_e32 v27, 0xffff0000, v13
	ds_write_b128 v32, v[24:27]
	v_lshlrev_b32_e32 v24, 16, v14
	v_and_b32_e32 v25, 0xffff0000, v14
	v_lshlrev_b32_e32 v26, 16, v15
	v_and_b32_e32 v27, 0xffff0000, v15
	ds_write_b128 v32, v[24:27] offset:16
	v_lshl_add_u32 v2, v88, 2, v2
	s_waitcnt vmcnt(1)
	v_lshlrev_b32_e32 v24, 16, v16
	v_and_b32_e32 v25, 0xffff0000, v16
	v_lshlrev_b32_e32 v26, 16, v17
	v_and_b32_e32 v27, 0xffff0000, v17
	ds_write_b128 v2, v[24:27]
	v_lshlrev_b32_e32 v24, 16, v18
	v_and_b32_e32 v25, 0xffff0000, v18
	v_lshlrev_b32_e32 v26, 16, v19
	v_and_b32_e32 v27, 0xffff0000, v19
	ds_write_b128 v2, v[24:27] offset:16
	v_lshlrev_b32_e32 v2, 2, v89
	v_add3_u32 v2, s41, v2, v90
	s_waitcnt vmcnt(1)
	ds_write_b128 v2, v[20:23] offset:512
	s_and_saveexec_b64 s[2:3], s[76:77]
	s_xor_b64 s[2:3], exec, s[2:3]
	s_cbranch_execz .LBB0_71
	s_and_saveexec_b64 s[20:21], s[78:79]
	v_add_u32_e32 v2, s41, v91
	v_add_u32_e32 v2, 0xfffd5d40, v2
	ds_write_b128 v2, v[4:7]
	s_or_b64 exec, exec, s[20:21]

.LBB0_74:
	s_cmpk_gt_u32 s40, 0xfd
	s_cbranch_scc1 .LBB0_65
	s_waitcnt vmcnt(1)
	v_lshl_add_u64 v[20:21], v[76:77], 0, s[0:1]
	global_load_dwordx4 v[12:15], v[72:73], off
	global_load_dwordx4 v[16:19], v[74:75], off
	s_nop 0
	global_load_dwordx4 v[20:23], v[20:21], off
	s_and_saveexec_b64 s[2:3], s[76:77]
	s_xor_b64 s[2:3], exec, s[2:3]
	s_cbranch_execz .LBB0_79
	s_and_saveexec_b64 s[20:21], s[78:79]
	s_cbranch_execz .LBB0_78
	global_load_dwordx4 v[4:7], v[70:71], off

.LBB0_149:
	s_or_b64 exec, exec, s[0:1]
	s_movk_i32 s0, 0x550
	v_lshrrev_b32_e32 v2, 2, v160
	v_mul_lo_u32 v91, v160, s0
	v_mul_lo_u32 v92, v2, s0
	s_lshl_b32 s0, s89, 6
	v_lshrrev_b32_e32 v1, 4, v160
	s_or_b32 s48, s8, s0
	s_lshl_b64 s[0:1], s[20:21], 16
	v_readlane_b32 s20, v254, 40
	v_bfi_b32 v0, 3, v1, v0
	v_and_b32_e32 v1, 15, v160
	s_add_u32 s0, s20, s0
	v_readlane_b32 s20, v254, 41
	v_add_u32_e32 v2, 0xffffff80, v160
	v_lshlrev_b32_e32 v93, 2, v1
	v_cmp_eq_u32_e64 s[2:3], 0, v1
	v_cmp_eq_u32_e64 s[30:31], 1, v1
	v_cmp_eq_u32_e64 s[70:71], 2, v1
	v_cmp_eq_u32_e64 s[40:41], 3, v1
	v_cmp_eq_u32_e64 s[42:43], 4, v1
	v_cmp_eq_u32_e64 s[44:45], 5, v1
	v_cmp_eq_u32_e64 s[46:47], 6, v1
	v_cmp_eq_u32_e64 s[58:59], 7, v1
	v_cmp_eq_u32_e64 s[60:61], 8, v1
	v_cmp_eq_u32_e64 s[62:63], 9, v1
	v_cmp_eq_u32_e64 s[64:65], 10, v1
	v_cmp_eq_u32_e64 s[66:67], 11, v1
	v_cmp_eq_u32_e64 s[68:69], 12, v1
	v_cmp_eq_u32_e32 vcc, 14, v1
	v_cmp_eq_u32_e64 s[38:39], 13, v1
	v_cmp_eq_u32_e64 s[4:5], 15, v1
	v_lshl_or_b32 v34, v1, 8, s48
	v_mov_b32_e32 v35, s9
	v_ashrrev_i32_e32 v1, 31, v0
	v_readlane_b32 s72, v254, 44
	s_addc_u32 s1, s20, s1
	v_lshl_add_u64 v[36:37], v[0:1], 2, v[34:35]
	v_readlane_b32 s86, v254, 58
	v_readlane_b32 s87, v254, 59
	v_lshl_add_u64 v[70:71], v[2:3], 4, s[0:1]
	v_and_b32_e32 v1, 0x7f, v160
	v_readlane_b32 s0, v254, 42
	v_lshlrev_b32_e32 v30, 4, v160
	v_readlane_b32 s80, v254, 52
	v_readlane_b32 s81, v254, 53
	v_lshl_add_u64 v[68:69], s[86:87], 0, v[36:37]
	v_lshl_or_b32 v36, v1, 4, s6
	v_mov_b32_e32 v37, s7
	s_add_u32 s0, s0, s8
	v_readlane_b32 s1, v254, 43
	v_and_b32_e32 v32, 0xffffffc0, v30
	v_lshl_add_u64 v[24:25], v[24:25], 0, v[36:37]
	s_mov_b64 s[80:81], 0x1000
	s_addc_u32 s1, s1, s9
	v_and_b32_e32 v1, 3, v160
	v_ashrrev_i32_e32 v33, 31, v32
	v_lshl_add_u64 v[72:73], v[24:25], 0, s[80:81]
	v_lshl_add_u64 v[24:25], v[26:27], 0, v[36:37]
	v_lshl_add_u64 v[76:77], v[28:29], 2, s[0:1]
	v_lshl_or_b32 v34, v1, 4, s48
	v_readlane_b32 s0, v254, 60
	v_readlane_b32 s73, v254, 45
	v_readlane_b32 s76, v254, 48
	v_readlane_b32 s77, v254, 49
	v_lshl_add_u64 v[74:75], v[24:25], 0, s[80:81]
	v_lshl_add_u64 v[24:25], v[32:33], 2, v[34:35]
	v_readlane_b32 s1, v254, 61
	v_mov_b32_e32 v30, 0
	s_mov_b32 s24, 0
	s_mov_b64 s[72:73], s[2:3]
	s_mov_b64 s[76:77], s[38:39]
	v_lshl_add_u64 v[78:79], s[0:1], 0, v[24:25]
	s_mov_b64 s[0:1], 0
	v_lshlrev_b32_e32 v1, 2, v31
	v_mov_b32_e32 v31, v30
	v_mov_b32_e32 v28, v30
	v_mov_b32_e32 v29, v30
	s_waitcnt lgkmcnt(0)
	s_barrier
	v_readlane_b32 s74, v254, 46
	v_readlane_b32 s75, v254, 47
	v_readlane_b32 s78, v254, 50
	v_readlane_b32 s79, v254, 51
	v_readlane_b32 s82, v254, 54
	v_readlane_b32 s83, v254, 55
	v_readlane_b32 s84, v254, 56
	v_readlane_b32 s85, v254, 57
	s_waitcnt vmcnt(0)
	s_branch .LBB0_152

.LBB0_151:
	s_bitcmp1_b32 s24, 0
	s_cselect_b32 s2, 0x5500, 0
	v_lshl_or_b32 v94, v93, 2, s2
	v_lshl_add_u32 v95, v0, 2, s2
	v_mov_b32_e32 v96, s2
	v_mul_u32_u24_e32 v46, 0x154, v93
	v_add_u32_e32 v47, v46, v96
	v_add_u32_e32 v46, v46, v95
	ds_read_b64 v[44:45], v47 offset:1344
	ds_read_b32 v48, v46 offset:1280
	ds_read_b128 v[110:113], v94
	ds_read_b128 v[126:129], v94 offset:1024
	ds_read_b128 v[114:117], v94 offset:256
	ds_read_b128 v[118:121], v94 offset:512
	ds_read_b128 v[122:125], v94 offset:768
	ds_read_b32 v130, v95 offset:1280
	s_mov_b64 s[2:3], 0x100
	s_mov_b64 s[20:21], 0x800
	s_waitcnt lgkmcnt(4)
	v_pk_mul_f32 v[24:25], v[28:29], v[110:111]
	v_pk_mul_f32 v[26:27], v[28:29], v[126:127]
	v_pk_fma_f32 v[24:25], v[30:31], v[112:113], v[24:25]
	v_pk_fma_f32 v[26:27], v[30:31], v[128:129], v[26:27]
	v_add_f32_e32 v34, v24, v25
	ds_read_b128 v[134:137], v94 offset:1360
	v_add_f32_e32 v50, v26, v27
	v_add_f32_dpp v34, v34, v34 quad_perm:[1,0,3,2] row_mask:0xf bank_mask:0xf bound_ctrl:1
	ds_read_b128 v[150:153], v94 offset:2384
	ds_read_b128 v[138:141], v94 offset:1616
	v_add_f32_dpp v34, v34, v34 quad_perm:[2,3,0,1] row_mask:0xf bank_mask:0xf bound_ctrl:1
	s_waitcnt lgkmcnt(3)
	v_pk_mul_f32 v[36:37], v[122:123], v[130:131] op_sel_hi:[1,0]
	v_pk_mul_f32 v[38:39], v[124:125], v[130:131] op_sel_hi:[1,0]
	v_add_f32_dpp v34, v34, v34 row_ror:4 row_mask:0xf bank_mask:0xf bound_ctrl:1
	v_pk_fma_f32 v[36:37], v[28:29], v[118:119], v[36:37]
	v_pk_fma_f32 v[38:39], v[30:31], v[120:121], v[38:39]
	v_add_f32_dpp v34, v34, v34 row_ror:8 row_mask:0xf bank_mask:0xf bound_ctrl:1
	ds_read_b128 v[142:145], v94 offset:1872
	ds_read_b128 v[146:149], v94 offset:2128
	v_pk_fma_f32 v[28:29], v[114:115], v[34:35], v[36:37] op_sel_hi:[1,0,1] neg_lo:[0,1,0] neg_hi:[0,1,0]
	v_pk_fma_f32 v[30:31], v[116:117], v[34:35], v[38:39] op_sel_hi:[1,0,1] neg_lo:[0,1,0] neg_hi:[0,1,0]
	v_cndmask_b32_e64 v42, 0, v34, s[72:73]
	ds_read_b32 v154, v95 offset:2640
	s_waitcnt lgkmcnt(4)
	v_pk_mul_f32 v[24:25], v[28:29], v[134:135]
	v_pk_mul_f32 v[26:27], v[28:29], v[150:151]
	v_pk_fma_f32 v[24:25], v[30:31], v[136:137], v[24:25]
	v_pk_fma_f32 v[26:27], v[30:31], v[152:153], v[26:27]
	v_add_f32_e32 v34, v24, v25
	ds_read_b128 v[110:113], v94 offset:2720
	v_add_f32_e32 v51, v26, v27
	v_add_f32_dpp v34, v34, v34 quad_perm:[1,0,3,2] row_mask:0xf bank_mask:0xf bound_ctrl:1
	ds_read_b128 v[126:129], v94 offset:3744
	ds_read_b128 v[114:117], v94 offset:2976
	v_add_f32_dpp v34, v34, v34 quad_perm:[2,3,0,1] row_mask:0xf bank_mask:0xf bound_ctrl:1
	s_waitcnt lgkmcnt(3)
	v_pk_mul_f32 v[36:37], v[146:147], v[154:155] op_sel_hi:[1,0]
	v_pk_mul_f32 v[38:39], v[148:149], v[154:155] op_sel_hi:[1,0]
	v_add_f32_dpp v34, v34, v34 row_ror:4 row_mask:0xf bank_mask:0xf bound_ctrl:1
	v_pk_fma_f32 v[36:37], v[28:29], v[142:143], v[36:37]
	v_pk_fma_f32 v[38:39], v[30:31], v[144:145], v[38:39]
	v_add_f32_dpp v34, v34, v34 row_ror:8 row_mask:0xf bank_mask:0xf bound_ctrl:1
	ds_read_b128 v[118:121], v94 offset:3232
	ds_read_b128 v[122:125], v94 offset:3488
	v_pk_fma_f32 v[28:29], v[138:139], v[34:35], v[36:37] op_sel_hi:[1,0,1] neg_lo:[0,1,0] neg_hi:[0,1,0]
	v_pk_fma_f32 v[30:31], v[140:141], v[34:35], v[38:39] op_sel_hi:[1,0,1] neg_lo:[0,1,0] neg_hi:[0,1,0]
	v_cndmask_b32_e64 v42, v42, v34, s[30:31]
	ds_read_b32 v130, v95 offset:4000
	s_waitcnt lgkmcnt(4)
	v_pk_mul_f32 v[24:25], v[28:29], v[110:111]
	v_pk_mul_f32 v[26:27], v[28:29], v[126:127]
	v_pk_fma_f32 v[24:25], v[30:31], v[112:113], v[24:25]
	v_pk_fma_f32 v[26:27], v[30:31], v[128:129], v[26:27]
	v_add_f32_e32 v34, v24, v25
	ds_read_b128 v[134:137], v94 offset:4080
	v_add_f32_e32 v52, v26, v27
	v_add_f32_dpp v34, v34, v34 quad_perm:[1,0,3,2] row_mask:0xf bank_mask:0xf bound_ctrl:1
	ds_read_b128 v[150:153], v94 offset:5104
	ds_read_b128 v[138:141], v94 offset:4336
	v_add_f32_dpp v34, v34, v34 quad_perm:[2,3,0,1] row_mask:0xf bank_mask:0xf bound_ctrl:1
	s_waitcnt lgkmcnt(3)
	v_pk_mul_f32 v[36:37], v[122:123], v[130:131] op_sel_hi:[1,0]
	v_pk_mul_f32 v[38:39], v[124:125], v[130:131] op_sel_hi:[1,0]
	v_add_f32_dpp v34, v34, v34 row_ror:4 row_mask:0xf bank_mask:0xf bound_ctrl:1
	v_pk_fma_f32 v[36:37], v[28:29], v[118:119], v[36:37]
	v_pk_fma_f32 v[38:39], v[30:31], v[120:121], v[38:39]
	v_add_f32_dpp v34, v34, v34 row_ror:8 row_mask:0xf bank_mask:0xf bound_ctrl:1
	ds_read_b128 v[142:145], v94 offset:4592
	ds_read_b128 v[146:149], v94 offset:4848
	v_pk_fma_f32 v[28:29], v[114:115], v[34:35], v[36:37] op_sel_hi:[1,0,1] neg_lo:[0,1,0] neg_hi:[0,1,0]
	v_pk_fma_f32 v[30:31], v[116:117], v[34:35], v[38:39] op_sel_hi:[1,0,1] neg_lo:[0,1,0] neg_hi:[0,1,0]
	v_cndmask_b32_e64 v42, v42, v34, s[70:71]
	ds_read_b32 v154, v95 offset:5360
	s_waitcnt lgkmcnt(4)
	v_pk_mul_f32 v[24:25], v[28:29], v[134:135]
	v_pk_mul_f32 v[26:27], v[28:29], v[150:151]
	v_pk_fma_f32 v[24:25], v[30:31], v[136:137], v[24:25]
	v_pk_fma_f32 v[26:27], v[30:31], v[152:153], v[26:27]
	v_add_f32_e32 v34, v24, v25
	ds_read_b128 v[110:113], v94 offset:5440
	v_add_f32_e32 v53, v26, v27
	v_add_f32_dpp v34, v34, v34 quad_perm:[1,0,3,2] row_mask:0xf bank_mask:0xf bound_ctrl:1
	ds_read_b128 v[126:129], v94 offset:6464
	ds_read_b128 v[114:117], v94 offset:5696
	v_add_f32_dpp v34, v34, v34 quad_perm:[2,3,0,1] row_mask:0xf bank_mask:0xf bound_ctrl:1
	s_waitcnt lgkmcnt(3)
	v_pk_mul_f32 v[36:37], v[146:147], v[154:155] op_sel_hi:[1,0]
	v_pk_mul_f32 v[38:39], v[148:149], v[154:155] op_sel_hi:[1,0]
	v_add_f32_dpp v34, v34, v34 row_ror:4 row_mask:0xf bank_mask:0xf bound_ctrl:1
	v_pk_fma_f32 v[36:37], v[28:29], v[142:143], v[36:37]
	v_pk_fma_f32 v[38:39], v[30:31], v[144:145], v[38:39]
	v_add_f32_dpp v34, v34, v34 row_ror:8 row_mask:0xf bank_mask:0xf bound_ctrl:1
	ds_read_b128 v[118:121], v94 offset:5952
	ds_read_b128 v[122:125], v94 offset:6208
	v_pk_fma_f32 v[28:29], v[138:139], v[34:35], v[36:37] op_sel_hi:[1,0,1] neg_lo:[0,1,0] neg_hi:[0,1,0]
	v_pk_fma_f32 v[30:31], v[140:141], v[34:35], v[38:39] op_sel_hi:[1,0,1] neg_lo:[0,1,0] neg_hi:[0,1,0]
	v_cndmask_b32_e64 v42, v42, v34, s[40:41]
	ds_read_b32 v130, v95 offset:6720
	s_waitcnt lgkmcnt(4)
	v_pk_mul_f32 v[24:25], v[28:29], v[110:111]
	v_pk_mul_f32 v[26:27], v[28:29], v[126:127]
	v_pk_fma_f32 v[24:25], v[30:31], v[112:113], v[24:25]
	v_pk_fma_f32 v[26:27], v[30:31], v[128:129], v[26:27]
	v_add_f32_e32 v34, v24, v25
	ds_read_b128 v[134:137], v94 offset:6800
	v_add_f32_e32 v54, v26, v27
	v_add_f32_dpp v34, v34, v34 quad_perm:[1,0,3,2] row_mask:0xf bank_mask:0xf bound_ctrl:1
	ds_read_b128 v[150:153], v94 offset:7824
	ds_read_b128 v[138:141], v94 offset:7056
	v_add_f32_dpp v34, v34, v34 quad_perm:[2,3,0,1] row_mask:0xf bank_mask:0xf bound_ctrl:1
	s_waitcnt lgkmcnt(3)
	v_pk_mul_f32 v[36:37], v[122:123], v[130:131] op_sel_hi:[1,0]
	v_pk_mul_f32 v[38:39], v[124:125], v[130:131] op_sel_hi:[1,0]
	v_add_f32_dpp v34, v34, v34 row_ror:4 row_mask:0xf bank_mask:0xf bound_ctrl:1
	v_pk_fma_f32 v[36:37], v[28:29], v[118:119], v[36:37]
	v_pk_fma_f32 v[38:39], v[30:31], v[120:121], v[38:39]
	v_add_f32_dpp v34, v34, v34 row_ror:8 row_mask:0xf bank_mask:0xf bound_ctrl:1
	ds_read_b128 v[142:145], v94 offset:7312
	ds_read_b128 v[146:149], v94 offset:7568
	v_pk_fma_f32 v[28:29], v[114:115], v[34:35], v[36:37] op_sel_hi:[1,0,1] neg_lo:[0,1,0] neg_hi:[0,1,0]
	v_pk_fma_f32 v[30:31], v[116:117], v[34:35], v[38:39] op_sel_hi:[1,0,1] neg_lo:[0,1,0] neg_hi:[0,1,0]
	v_cndmask_b32_e64 v42, v42, v34, s[42:43]
	ds_read_b32 v154, v95 offset:8080
	s_waitcnt lgkmcnt(4)
	v_pk_mul_f32 v[24:25], v[28:29], v[134:135]
	v_pk_mul_f32 v[26:27], v[28:29], v[150:151]
	v_pk_fma_f32 v[24:25], v[30:31], v[136:137], v[24:25]
	v_pk_fma_f32 v[26:27], v[30:31], v[152:153], v[26:27]
	v_add_f32_e32 v34, v24, v25
	ds_read_b128 v[110:113], v94 offset:8160
	v_add_f32_e32 v55, v26, v27
	v_add_f32_dpp v34, v34, v34 quad_perm:[1,0,3,2] row_mask:0xf bank_mask:0xf bound_ctrl:1
	ds_read_b128 v[126:129], v94 offset:9184
	ds_read_b128 v[114:117], v94 offset:8416
	v_add_f32_dpp v34, v34, v34 quad_perm:[2,3,0,1] row_mask:0xf bank_mask:0xf bound_ctrl:1
	s_waitcnt lgkmcnt(3)
	v_pk_mul_f32 v[36:37], v[146:147], v[154:155] op_sel_hi:[1,0]
	v_pk_mul_f32 v[38:39], v[148:149], v[154:155] op_sel_hi:[1,0]
	v_add_f32_dpp v34, v34, v34 row_ror:4 row_mask:0xf bank_mask:0xf bound_ctrl:1
	v_pk_fma_f32 v[36:37], v[28:29], v[142:143], v[36:37]
	v_pk_fma_f32 v[38:39], v[30:31], v[144:145], v[38:39]
	v_add_f32_dpp v34, v34, v34 row_ror:8 row_mask:0xf bank_mask:0xf bound_ctrl:1
	ds_read_b128 v[118:121], v94 offset:8672
	ds_read_b128 v[122:125], v94 offset:8928
	v_pk_fma_f32 v[28:29], v[138:139], v[34:35], v[36:37] op_sel_hi:[1,0,1] neg_lo:[0,1,0] neg_hi:[0,1,0]
	v_pk_fma_f32 v[30:31], v[140:141], v[34:35], v[38:39] op_sel_hi:[1,0,1] neg_lo:[0,1,0] neg_hi:[0,1,0]
	v_cndmask_b32_e64 v42, v42, v34, s[44:45]
	ds_read_b32 v130, v95 offset:9440
	s_waitcnt lgkmcnt(4)
	v_pk_mul_f32 v[24:25], v[28:29], v[110:111]
	v_pk_mul_f32 v[26:27], v[28:29], v[126:127]
	v_pk_fma_f32 v[24:25], v[30:31], v[112:113], v[24:25]
	v_pk_fma_f32 v[26:27], v[30:31], v[128:129], v[26:27]
	v_add_f32_e32 v34, v24, v25
	ds_read_b128 v[134:137], v94 offset:9520
	v_add_f32_e32 v56, v26, v27
	v_add_f32_dpp v34, v34, v34 quad_perm:[1,0,3,2] row_mask:0xf bank_mask:0xf bound_ctrl:1
	ds_read_b128 v[150:153], v94 offset:10544
	ds_read_b128 v[138:141], v94 offset:9776
	v_add_f32_dpp v34, v34, v34 quad_perm:[2,3,0,1] row_mask:0xf bank_mask:0xf bound_ctrl:1
	s_waitcnt lgkmcnt(3)
	v_pk_mul_f32 v[36:37], v[122:123], v[130:131] op_sel_hi:[1,0]
	v_pk_mul_f32 v[38:39], v[124:125], v[130:131] op_sel_hi:[1,0]
	v_add_f32_dpp v34, v34, v34 row_ror:4 row_mask:0xf bank_mask:0xf bound_ctrl:1
	v_pk_fma_f32 v[36:37], v[28:29], v[118:119], v[36:37]
	v_pk_fma_f32 v[38:39], v[30:31], v[120:121], v[38:39]
	v_add_f32_dpp v34, v34, v34 row_ror:8 row_mask:0xf bank_mask:0xf bound_ctrl:1
	ds_read_b128 v[142:145], v94 offset:10032
	ds_read_b128 v[146:149], v94 offset:10288
	v_pk_fma_f32 v[28:29], v[114:115], v[34:35], v[36:37] op_sel_hi:[1,0,1] neg_lo:[0,1,0] neg_hi:[0,1,0]
	v_pk_fma_f32 v[30:31], v[116:117], v[34:35], v[38:39] op_sel_hi:[1,0,1] neg_lo:[0,1,0] neg_hi:[0,1,0]
	v_cndmask_b32_e64 v42, v42, v34, s[46:47]
	ds_read_b32 v154, v95 offset:10800
	s_waitcnt lgkmcnt(4)
	v_pk_mul_f32 v[24:25], v[28:29], v[134:135]
	v_pk_mul_f32 v[26:27], v[28:29], v[150:151]
	v_pk_fma_f32 v[24:25], v[30:31], v[136:137], v[24:25]
	v_pk_fma_f32 v[26:27], v[30:31], v[152:153], v[26:27]
	v_add_f32_e32 v34, v24, v25
	ds_read_b128 v[110:113], v94 offset:10880
	v_add_f32_e32 v57, v26, v27
	v_add_f32_dpp v34, v34, v34 quad_perm:[1,0,3,2] row_mask:0xf bank_mask:0xf bound_ctrl:1
	ds_read_b128 v[126:129], v94 offset:11904
	ds_read_b128 v[114:117], v94 offset:11136
	v_add_f32_dpp v34, v34, v34 quad_perm:[2,3,0,1] row_mask:0xf bank_mask:0xf bound_ctrl:1
	s_waitcnt lgkmcnt(3)
	v_pk_mul_f32 v[36:37], v[146:147], v[154:155] op_sel_hi:[1,0]
	v_pk_mul_f32 v[38:39], v[148:149], v[154:155] op_sel_hi:[1,0]
	v_add_f32_dpp v34, v34, v34 row_ror:4 row_mask:0xf bank_mask:0xf bound_ctrl:1
	v_pk_fma_f32 v[36:37], v[28:29], v[142:143], v[36:37]
	v_pk_fma_f32 v[38:39], v[30:31], v[144:145], v[38:39]
	v_add_f32_dpp v34, v34, v34 row_ror:8 row_mask:0xf bank_mask:0xf bound_ctrl:1
	ds_read_b128 v[118:121], v94 offset:11392
	ds_read_b128 v[122:125], v94 offset:11648
	v_pk_fma_f32 v[28:29], v[138:139], v[34:35], v[36:37] op_sel_hi:[1,0,1] neg_lo:[0,1,0] neg_hi:[0,1,0]
	v_pk_fma_f32 v[30:31], v[140:141], v[34:35], v[38:39] op_sel_hi:[1,0,1] neg_lo:[0,1,0] neg_hi:[0,1,0]
	v_cndmask_b32_e64 v42, v42, v34, s[58:59]
	ds_read_b32 v130, v95 offset:12160
	s_waitcnt lgkmcnt(4)
	v_pk_mul_f32 v[24:25], v[28:29], v[110:111]
	v_pk_mul_f32 v[26:27], v[28:29], v[126:127]
	v_pk_fma_f32 v[24:25], v[30:31], v[112:113], v[24:25]
	v_pk_fma_f32 v[26:27], v[30:31], v[128:129], v[26:27]
	v_add_f32_e32 v34, v24, v25
	ds_read_b128 v[134:137], v94 offset:12240
	v_add_f32_e32 v58, v26, v27
	v_add_f32_dpp v34, v34, v34 quad_perm:[1,0,3,2] row_mask:0xf bank_mask:0xf bound_ctrl:1
	ds_read_b128 v[150:153], v94 offset:13264
	ds_read_b128 v[138:141], v94 offset:12496
	v_add_f32_dpp v34, v34, v34 quad_perm:[2,3,0,1] row_mask:0xf bank_mask:0xf bound_ctrl:1
	s_waitcnt lgkmcnt(3)
	v_pk_mul_f32 v[36:37], v[122:123], v[130:131] op_sel_hi:[1,0]
	v_pk_mul_f32 v[38:39], v[124:125], v[130:131] op_sel_hi:[1,0]
	v_add_f32_dpp v34, v34, v34 row_ror:4 row_mask:0xf bank_mask:0xf bound_ctrl:1
	v_pk_fma_f32 v[36:37], v[28:29], v[118:119], v[36:37]
	v_pk_fma_f32 v[38:39], v[30:31], v[120:121], v[38:39]
	v_add_f32_dpp v34, v34, v34 row_ror:8 row_mask:0xf bank_mask:0xf bound_ctrl:1
	ds_read_b128 v[142:145], v94 offset:12752
	ds_read_b128 v[146:149], v94 offset:13008
	v_pk_fma_f32 v[28:29], v[114:115], v[34:35], v[36:37] op_sel_hi:[1,0,1] neg_lo:[0,1,0] neg_hi:[0,1,0]
	v_pk_fma_f32 v[30:31], v[116:117], v[34:35], v[38:39] op_sel_hi:[1,0,1] neg_lo:[0,1,0] neg_hi:[0,1,0]
	v_cndmask_b32_e64 v42, v42, v34, s[60:61]
	ds_read_b32 v154, v95 offset:13520
	s_waitcnt lgkmcnt(4)
	v_pk_mul_f32 v[24:25], v[28:29], v[134:135]
	v_pk_mul_f32 v[26:27], v[28:29], v[150:151]
	v_pk_fma_f32 v[24:25], v[30:31], v[136:137], v[24:25]
	v_pk_fma_f32 v[26:27], v[30:31], v[152:153], v[26:27]
	v_add_f32_e32 v34, v24, v25
	ds_read_b128 v[110:113], v94 offset:13600
	v_add_f32_e32 v59, v26, v27
	v_add_f32_dpp v34, v34, v34 quad_perm:[1,0,3,2] row_mask:0xf bank_mask:0xf bound_ctrl:1
	ds_read_b128 v[126:129], v94 offset:14624
	ds_read_b128 v[114:117], v94 offset:13856
	v_add_f32_dpp v34, v34, v34 quad_perm:[2,3,0,1] row_mask:0xf bank_mask:0xf bound_ctrl:1
	s_waitcnt lgkmcnt(3)
	v_pk_mul_f32 v[36:37], v[146:147], v[154:155] op_sel_hi:[1,0]
	v_pk_mul_f32 v[38:39], v[148:149], v[154:155] op_sel_hi:[1,0]
	v_add_f32_dpp v34, v34, v34 row_ror:4 row_mask:0xf bank_mask:0xf bound_ctrl:1
	v_pk_fma_f32 v[36:37], v[28:29], v[142:143], v[36:37]
	v_pk_fma_f32 v[38:39], v[30:31], v[144:145], v[38:39]
	v_add_f32_dpp v34, v34, v34 row_ror:8 row_mask:0xf bank_mask:0xf bound_ctrl:1
	ds_read_b128 v[118:121], v94 offset:14112
	ds_read_b128 v[122:125], v94 offset:14368
	v_pk_fma_f32 v[28:29], v[138:139], v[34:35], v[36:37] op_sel_hi:[1,0,1] neg_lo:[0,1,0] neg_hi:[0,1,0]
	v_pk_fma_f32 v[30:31], v[140:141], v[34:35], v[38:39] op_sel_hi:[1,0,1] neg_lo:[0,1,0] neg_hi:[0,1,0]
	v_cndmask_b32_e64 v42, v42, v34, s[62:63]
	ds_read_b32 v130, v95 offset:14880
	s_waitcnt lgkmcnt(4)
	v_pk_mul_f32 v[24:25], v[28:29], v[110:111]
	v_pk_mul_f32 v[26:27], v[28:29], v[126:127]
	v_pk_fma_f32 v[24:25], v[30:31], v[112:113], v[24:25]
	v_pk_fma_f32 v[26:27], v[30:31], v[128:129], v[26:27]
	v_add_f32_e32 v34, v24, v25
	ds_read_b128 v[134:137], v94 offset:14960
	v_add_f32_e32 v60, v26, v27
	v_add_f32_dpp v34, v34, v34 quad_perm:[1,0,3,2] row_mask:0xf bank_mask:0xf bound_ctrl:1
	ds_read_b128 v[150:153], v94 offset:15984
	ds_read_b128 v[138:141], v94 offset:15216
	v_add_f32_dpp v34, v34, v34 quad_perm:[2,3,0,1] row_mask:0xf bank_mask:0xf bound_ctrl:1
	s_waitcnt lgkmcnt(3)
	v_pk_mul_f32 v[36:37], v[122:123], v[130:131] op_sel_hi:[1,0]
	v_pk_mul_f32 v[38:39], v[124:125], v[130:131] op_sel_hi:[1,0]
	v_add_f32_dpp v34, v34, v34 row_ror:4 row_mask:0xf bank_mask:0xf bound_ctrl:1
	v_pk_fma_f32 v[36:37], v[28:29], v[118:119], v[36:37]
	v_pk_fma_f32 v[38:39], v[30:31], v[120:121], v[38:39]
	v_add_f32_dpp v34, v34, v34 row_ror:8 row_mask:0xf bank_mask:0xf bound_ctrl:1
	ds_read_b128 v[142:145], v94 offset:15472
	ds_read_b128 v[146:149], v94 offset:15728
	v_pk_fma_f32 v[28:29], v[114:115], v[34:35], v[36:37] op_sel_hi:[1,0,1] neg_lo:[0,1,0] neg_hi:[0,1,0]
	v_pk_fma_f32 v[30:31], v[116:117], v[34:35], v[38:39] op_sel_hi:[1,0,1] neg_lo:[0,1,0] neg_hi:[0,1,0]
	v_cndmask_b32_e64 v42, v42, v34, s[64:65]
	ds_read_b32 v154, v95 offset:16240
	s_waitcnt lgkmcnt(4)
	v_pk_mul_f32 v[24:25], v[28:29], v[134:135]
	v_pk_mul_f32 v[26:27], v[28:29], v[150:151]
	v_pk_fma_f32 v[24:25], v[30:31], v[136:137], v[24:25]
	v_pk_fma_f32 v[26:27], v[30:31], v[152:153], v[26:27]
	v_add_f32_e32 v34, v24, v25
	ds_read_b128 v[110:113], v94 offset:16320
	v_add_f32_e32 v61, v26, v27
	v_add_f32_dpp v34, v34, v34 quad_perm:[1,0,3,2] row_mask:0xf bank_mask:0xf bound_ctrl:1
	ds_read_b128 v[126:129], v94 offset:17344
	ds_read_b128 v[114:117], v94 offset:16576
	v_add_f32_dpp v34, v34, v34 quad_perm:[2,3,0,1] row_mask:0xf bank_mask:0xf bound_ctrl:1
	s_waitcnt lgkmcnt(3)
	v_pk_mul_f32 v[36:37], v[146:147], v[154:155] op_sel_hi:[1,0]
	v_pk_mul_f32 v[38:39], v[148:149], v[154:155] op_sel_hi:[1,0]
	v_add_f32_dpp v34, v34, v34 row_ror:4 row_mask:0xf bank_mask:0xf bound_ctrl:1
	v_pk_fma_f32 v[36:37], v[28:29], v[142:143], v[36:37]
	v_pk_fma_f32 v[38:39], v[30:31], v[144:145], v[38:39]
	v_add_f32_dpp v34, v34, v34 row_ror:8 row_mask:0xf bank_mask:0xf bound_ctrl:1
	ds_read_b128 v[118:121], v94 offset:16832
	ds_read_b128 v[122:125], v94 offset:17088
	v_pk_fma_f32 v[28:29], v[138:139], v[34:35], v[36:37] op_sel_hi:[1,0,1] neg_lo:[0,1,0] neg_hi:[0,1,0]
	v_pk_fma_f32 v[30:31], v[140:141], v[34:35], v[38:39] op_sel_hi:[1,0,1] neg_lo:[0,1,0] neg_hi:[0,1,0]
	v_cndmask_b32_e64 v42, v42, v34, s[66:67]
	ds_read_b32 v130, v95 offset:17600
	s_waitcnt lgkmcnt(4)
	v_pk_mul_f32 v[24:25], v[28:29], v[110:111]
	v_pk_mul_f32 v[26:27], v[28:29], v[126:127]
	v_pk_fma_f32 v[24:25], v[30:31], v[112:113], v[24:25]
	v_pk_fma_f32 v[26:27], v[30:31], v[128:129], v[26:27]
	v_add_f32_e32 v34, v24, v25
	ds_read_b128 v[134:137], v94 offset:17680
	v_add_f32_e32 v62, v26, v27
	v_add_f32_dpp v34, v34, v34 quad_perm:[1,0,3,2] row_mask:0xf bank_mask:0xf bound_ctrl:1
	ds_read_b128 v[150:153], v94 offset:18704
	ds_read_b128 v[138:141], v94 offset:17936
	v_add_f32_dpp v34, v34, v34 quad_perm:[2,3,0,1] row_mask:0xf bank_mask:0xf bound_ctrl:1
	s_waitcnt lgkmcnt(3)
	v_pk_mul_f32 v[36:37], v[122:123], v[130:131] op_sel_hi:[1,0]
	v_pk_mul_f32 v[38:39], v[124:125], v[130:131] op_sel_hi:[1,0]
	v_add_f32_dpp v34, v34, v34 row_ror:4 row_mask:0xf bank_mask:0xf bound_ctrl:1
	v_pk_fma_f32 v[36:37], v[28:29], v[118:119], v[36:37]
	v_pk_fma_f32 v[38:39], v[30:31], v[120:121], v[38:39]
	v_add_f32_dpp v34, v34, v34 row_ror:8 row_mask:0xf bank_mask:0xf bound_ctrl:1
	ds_read_b128 v[142:145], v94 offset:18192
	ds_read_b128 v[146:149], v94 offset:18448
	v_pk_fma_f32 v[28:29], v[114:115], v[34:35], v[36:37] op_sel_hi:[1,0,1] neg_lo:[0,1,0] neg_hi:[0,1,0]
	v_pk_fma_f32 v[30:31], v[116:117], v[34:35], v[38:39] op_sel_hi:[1,0,1] neg_lo:[0,1,0] neg_hi:[0,1,0]
	v_cndmask_b32_e64 v42, v42, v34, s[68:69]
	ds_read_b32 v154, v95 offset:18960
	s_waitcnt lgkmcnt(4)
	v_pk_mul_f32 v[24:25], v[28:29], v[134:135]
	v_pk_mul_f32 v[26:27], v[28:29], v[150:151]
	v_pk_fma_f32 v[24:25], v[30:31], v[136:137], v[24:25]
	v_pk_fma_f32 v[26:27], v[30:31], v[152:153], v[26:27]
	v_add_f32_e32 v34, v24, v25
	ds_read_b128 v[110:113], v94 offset:19040
	v_add_f32_e32 v63, v26, v27
	v_add_f32_dpp v34, v34, v34 quad_perm:[1,0,3,2] row_mask:0xf bank_mask:0xf bound_ctrl:1
	ds_read_b128 v[126:129], v94 offset:20064
	ds_read_b128 v[114:117], v94 offset:19296
	v_add_f32_dpp v34, v34, v34 quad_perm:[2,3,0,1] row_mask:0xf bank_mask:0xf bound_ctrl:1
	s_waitcnt lgkmcnt(3)
	v_pk_mul_f32 v[36:37], v[146:147], v[154:155] op_sel_hi:[1,0]
	v_pk_mul_f32 v[38:39], v[148:149], v[154:155] op_sel_hi:[1,0]
	v_add_f32_dpp v34, v34, v34 row_ror:4 row_mask:0xf bank_mask:0xf bound_ctrl:1
	v_pk_fma_f32 v[36:37], v[28:29], v[142:143], v[36:37]
	v_pk_fma_f32 v[38:39], v[30:31], v[144:145], v[38:39]
	v_add_f32_dpp v34, v34, v34 row_ror:8 row_mask:0xf bank_mask:0xf bound_ctrl:1
	ds_read_b128 v[118:121], v94 offset:19552
	ds_read_b128 v[122:125], v94 offset:19808
	v_pk_fma_f32 v[28:29], v[138:139], v[34:35], v[36:37] op_sel_hi:[1,0,1] neg_lo:[0,1,0] neg_hi:[0,1,0]
	v_pk_fma_f32 v[30:31], v[140:141], v[34:35], v[38:39] op_sel_hi:[1,0,1] neg_lo:[0,1,0] neg_hi:[0,1,0]
	v_cndmask_b32_e64 v42, v42, v34, s[76:77]
	ds_read_b32 v130, v95 offset:20320
	s_waitcnt lgkmcnt(4)
	v_pk_mul_f32 v[24:25], v[28:29], v[110:111]
	v_pk_mul_f32 v[26:27], v[28:29], v[126:127]
	v_pk_fma_f32 v[24:25], v[30:31], v[112:113], v[24:25]
	v_pk_fma_f32 v[26:27], v[30:31], v[128:129], v[26:27]
	v_add_f32_e32 v34, v24, v25
	ds_read_b128 v[134:137], v94 offset:20400
	v_add_f32_e32 v64, v26, v27
	v_add_f32_dpp v34, v34, v34 quad_perm:[1,0,3,2] row_mask:0xf bank_mask:0xf bound_ctrl:1
	ds_read_b128 v[150:153], v94 offset:21424
	ds_read_b128 v[138:141], v94 offset:20656
	v_add_f32_dpp v34, v34, v34 quad_perm:[2,3,0,1] row_mask:0xf bank_mask:0xf bound_ctrl:1
	s_waitcnt lgkmcnt(3)
	v_pk_mul_f32 v[36:37], v[122:123], v[130:131] op_sel_hi:[1,0]
	v_pk_mul_f32 v[38:39], v[124:125], v[130:131] op_sel_hi:[1,0]
	v_add_f32_dpp v34, v34, v34 row_ror:4 row_mask:0xf bank_mask:0xf bound_ctrl:1
	v_pk_fma_f32 v[36:37], v[28:29], v[118:119], v[36:37]
	v_pk_fma_f32 v[38:39], v[30:31], v[120:121], v[38:39]
	v_add_f32_dpp v34, v34, v34 row_ror:8 row_mask:0xf bank_mask:0xf bound_ctrl:1
	ds_read_b128 v[142:145], v94 offset:20912
	ds_read_b128 v[146:149], v94 offset:21168
	v_pk_fma_f32 v[28:29], v[114:115], v[34:35], v[36:37] op_sel_hi:[1,0,1] neg_lo:[0,1,0] neg_hi:[0,1,0]
	v_pk_fma_f32 v[30:31], v[116:117], v[34:35], v[38:39] op_sel_hi:[1,0,1] neg_lo:[0,1,0] neg_hi:[0,1,0]
	v_cndmask_b32_e32 v42, v42, v34, vcc
	ds_read_b32 v154, v95 offset:21680
	s_waitcnt lgkmcnt(4)
	v_pk_mul_f32 v[24:25], v[28:29], v[134:135]
	v_pk_mul_f32 v[26:27], v[28:29], v[150:151]
	v_pk_fma_f32 v[24:25], v[30:31], v[136:137], v[24:25]
	v_pk_fma_f32 v[26:27], v[30:31], v[152:153], v[26:27]
	v_add_f32_e32 v34, v24, v25
	v_lshl_add_u64 v[70:71], v[70:71], 0, s[2:3]
	v_add_f32_e32 v65, v26, v27
	v_add_f32_dpp v34, v34, v34 quad_perm:[1,0,3,2] row_mask:0xf bank_mask:0xf bound_ctrl:1
	v_lshl_add_u64 v[72:73], v[72:73], 0, s[20:21]
	v_lshl_add_u64 v[74:75], v[74:75], 0, s[20:21]
	v_add_f32_dpp v34, v34, v34 quad_perm:[2,3,0,1] row_mask:0xf bank_mask:0xf bound_ctrl:1
	s_waitcnt lgkmcnt(0)
	v_pk_mul_f32 v[36:37], v[146:147], v[154:155] op_sel_hi:[1,0]
	v_pk_mul_f32 v[38:39], v[148:149], v[154:155] op_sel_hi:[1,0]
	v_add_f32_dpp v34, v34, v34 row_ror:4 row_mask:0xf bank_mask:0xf bound_ctrl:1
	v_pk_fma_f32 v[36:37], v[28:29], v[142:143], v[36:37]
	v_pk_fma_f32 v[38:39], v[30:31], v[144:145], v[38:39]
	v_add_f32_dpp v34, v34, v34 row_ror:8 row_mask:0xf bank_mask:0xf bound_ctrl:1
	v_pk_fma_f32 v[28:29], v[138:139], v[34:35], v[36:37] op_sel_hi:[1,0,1] neg_lo:[0,1,0] neg_hi:[0,1,0]
	v_pk_fma_f32 v[30:31], v[140:141], v[34:35], v[38:39] op_sel_hi:[1,0,1] neg_lo:[0,1,0] neg_hi:[0,1,0]
	v_cndmask_b32_e64 v42, v42, v34, s[4:5]
	v_add_f32_dpp v50, v50, v50 row_ror:8 row_mask:0xf bank_mask:0xf bound_ctrl:1
	v_add_f32_dpp v51, v51, v51 row_ror:8 row_mask:0xf bank_mask:0xf bound_ctrl:1
	v_add_f32_dpp v52, v52, v52 row_ror:8 row_mask:0xf bank_mask:0xf bound_ctrl:1
	v_add_f32_dpp v53, v53, v53 row_ror:8 row_mask:0xf bank_mask:0xf bound_ctrl:1
	v_add_f32_dpp v54, v54, v54 row_ror:8 row_mask:0xf bank_mask:0xf bound_ctrl:1
	v_add_f32_dpp v55, v55, v55 row_ror:8 row_mask:0xf bank_mask:0xf bound_ctrl:1
	v_add_f32_dpp v56, v56, v56 row_ror:8 row_mask:0xf bank_mask:0xf bound_ctrl:1
	v_add_f32_dpp v57, v57, v57 row_ror:8 row_mask:0xf bank_mask:0xf bound_ctrl:1
	v_add_f32_dpp v50, v58, v58 row_ror:8 row_mask:0xf bank_mask:0xc bound_ctrl:1
	v_add_f32_dpp v51, v59, v59 row_ror:8 row_mask:0xf bank_mask:0xc bound_ctrl:1
	v_add_f32_dpp v52, v60, v60 row_ror:8 row_mask:0xf bank_mask:0xc bound_ctrl:1
	v_add_f32_dpp v53, v61, v61 row_ror:8 row_mask:0xf bank_mask:0xc bound_ctrl:1
	v_add_f32_dpp v54, v62, v62 row_ror:8 row_mask:0xf bank_mask:0xc bound_ctrl:1
	v_add_f32_dpp v55, v63, v63 row_ror:8 row_mask:0xf bank_mask:0xc bound_ctrl:1
	v_add_f32_dpp v56, v64, v64 row_ror:8 row_mask:0xf bank_mask:0xc bound_ctrl:1
	v_add_f32_dpp v57, v65, v65 row_ror:8 row_mask:0xf bank_mask:0xc bound_ctrl:1
	s_mov_b32 s2, 0xcccccccc
	s_mov_b32 s3, 0xcccccccc
	v_add_f32_dpp v50, v50, v50 row_half_mirror row_mask:0xf bank_mask:0x5 bound_ctrl:1
	v_add_f32_dpp v51, v51, v51 row_half_mirror row_mask:0xf bank_mask:0x5 bound_ctrl:1
	v_add_f32_dpp v52, v52, v52 row_half_mirror row_mask:0xf bank_mask:0x5 bound_ctrl:1
	v_add_f32_dpp v53, v53, v53 row_half_mirror row_mask:0xf bank_mask:0x5 bound_ctrl:1
	s_mov_b32 s20, 0xaaaaaaaa
	s_mov_b32 s21, 0xaaaaaaaa
	v_add_f32_dpp v50, v54, v54 row_half_mirror row_mask:0xf bank_mask:0xa bound_ctrl:1
	v_add_f32_dpp v51, v55, v55 row_half_mirror row_mask:0xf bank_mask:0xa bound_ctrl:1
	v_add_f32_dpp v52, v56, v56 row_half_mirror row_mask:0xf bank_mask:0xa bound_ctrl:1
	v_add_f32_dpp v53, v57, v57 row_half_mirror row_mask:0xf bank_mask:0xa bound_ctrl:1
	v_cndmask_b32_e64 v58, v52, v50, s[2:3]
	v_cndmask_b32_e64 v59, v53, v51, s[2:3]
	v_cndmask_b32_e64 v60, v50, v52, s[2:3]
	v_cndmask_b32_e64 v61, v51, v53, s[2:3]
	v_add_f32_dpp v50, v58, v60 quad_perm:[2,3,0,1] row_mask:0xf bank_mask:0xf bound_ctrl:1
	v_add_f32_dpp v51, v59, v61 quad_perm:[2,3,0,1] row_mask:0xf bank_mask:0xf bound_ctrl:1
	v_lshl_add_u64 v[24:25], v[68:69], 0, s[0:1]
	s_add_u32 s0, s0, 0x1000
	s_addc_u32 s1, s1, 0
	v_cndmask_b32_e64 v58, v51, v50, s[20:21]
	v_cndmask_b32_e64 v60, v50, v51, s[20:21]
	s_mov_b32 s24, s38
	s_cmp_lg_u32 s0, 0x54000
	v_add_f32_dpp v43, v58, v60 quad_perm:[1,0,3,2] row_mask:0xf bank_mask:0xf bound_ctrl:1
	v_fma_f32 v40, -v44, v42, v43
	v_fmac_f32_e32 v40, v48, v45
	global_store_dword v[24:25], v40, off
	s_barrier
	s_cbranch_scc0 .LBB0_233
.LBB0_152:
	s_add_i32 s38, s24, 1
	s_cmpk_gt_u32 s24, 0x52
	s_cbranch_scc1 .LBB0_160
	s_bitcmp1_b32 s38, 0
	s_cselect_b32 s39, 0x5500, 0
	v_lshlrev_b32_e32 v2, 2, v85
	v_add3_u32 v2, s39, v2, v86
	v_lshl_add_u32 v32, v87, 2, v2
	s_waitcnt vmcnt(1)
	v_lshlrev_b32_e32 v24, 16, v12
	v_and_b32_e32 v25, 0xffff0000, v12
	v_lshlrev_b32_e32 v26, 16, v13
	v_and_b32_e32 v27, 0xffff0000, v13
	ds_write_b128 v32, v[24:27]
	v_lshlrev_b32_e32 v24, 16, v14
	v_and_b32_e32 v25, 0xffff0000, v14
	v_lshlrev_b32_e32 v26, 16, v15
	v_and_b32_e32 v27, 0xffff0000, v15
	ds_write_b128 v32, v[24:27] offset:16
	v_lshl_add_u32 v2, v88, 2, v2
	s_waitcnt vmcnt(1)
	v_lshlrev_b32_e32 v24, 16, v16
	v_and_b32_e32 v25, 0xffff0000, v16
	v_lshlrev_b32_e32 v26, 16, v17
	v_and_b32_e32 v27, 0xffff0000, v17
	ds_write_b128 v2, v[24:27]
	v_lshlrev_b32_e32 v24, 16, v18
	v_and_b32_e32 v25, 0xffff0000, v18
	v_lshlrev_b32_e32 v26, 16, v19
	v_and_b32_e32 v27, 0xffff0000, v19
	ds_write_b128 v2, v[24:27] offset:16
	v_lshlrev_b32_e32 v2, 2, v89
	v_add3_u32 v2, s39, v2, v90
	s_waitcnt vmcnt(1)
	ds_write_b128 v2, v[20:23] offset:512
	s_mov_b64 s[2:3], exec
	v_readlane_b32 s20, v255, 21
	v_readlane_b32 s21, v255, 22
	s_and_b64 s[20:21], s[2:3], s[20:21]
	s_xor_b64 s[2:3], s[20:21], s[2:3]
	s_mov_b64 exec, s[20:21]
	s_cbranch_execz .LBB0_157
	s_mov_b64 s[20:21], exec
	v_readlane_b32 s48, v255, 23
	v_readlane_b32 s49, v255, 24
	s_and_b64 s[48:49], s[20:21], s[48:49]
	s_mov_b64 exec, s[48:49]
	v_add_u32_e32 v2, s39, v91
	v_add_u32_e32 v2, 0xfffd5d40, v2
	ds_write_b128 v2, v[4:7]
	s_or_b64 exec, exec, s[20:21]

.LBB0_160:
	s_cmpk_gt_u32 s24, 0x51
	s_cbranch_scc1 .LBB0_151
	s_waitcnt vmcnt(1)
	v_lshl_add_u64 v[20:21], v[76:77], 0, s[0:1]
	global_load_dwordx4 v[12:15], v[72:73], off
	global_load_dwordx4 v[16:19], v[74:75], off
	s_nop 0
	global_load_dwordx4 v[20:23], v[20:21], off
	s_mov_b64 s[2:3], exec
	v_readlane_b32 s20, v255, 21
	v_readlane_b32 s21, v255, 22
	s_and_b64 s[20:21], s[2:3], s[20:21]
	s_xor_b64 s[2:3], s[20:21], s[2:3]
	s_mov_b64 exec, s[20:21]
	s_cbranch_execz .LBB0_165
	s_mov_b64 s[20:21], exec
	v_readlane_b32 s48, v255, 23
	v_readlane_b32 s49, v255, 24
	s_and_b64 s[48:49], s[20:21], s[48:49]
	s_mov_b64 exec, s[48:49]
	s_cbranch_execz .LBB0_164
	global_load_dwordx4 v[4:7], v[70:71], off

.Lg16_loop_g0a:
	ds_read_b128 v[152:155], v216 offset:4096
	ds_read_b128 v[164:167], v216 offset:5120
	ds_read_b128 v[168:171], v216 offset:6144
	ds_read_b128 v[212:215], v216 offset:7168
	s_nop 0
	s_waitcnt lgkmcnt(4)
	v_mfma_f32_16x16x32_bf16 v[100:103], v[132:135], v[240:243], v[100:103]
	v_mfma_f32_16x16x32_bf16 v[104:107], v[136:139], v[240:243], v[104:107]
	v_mfma_f32_16x16x32_bf16 v[108:111], v[140:143], v[240:243], v[108:111]
	v_mfma_f32_16x16x32_bf16 v[112:115], v[144:147], v[240:243], v[112:115]
	v_mfma_f32_16x16x32_bf16 v[116:119], v[132:135], v[244:247], v[116:119]
	v_mfma_f32_16x16x32_bf16 v[120:123], v[136:139], v[244:247], v[120:123]
	v_mfma_f32_16x16x32_bf16 v[124:127], v[140:143], v[244:247], v[124:127]
	v_mfma_f32_16x16x32_bf16 v[128:131], v[144:147], v[244:247], v[128:131]
	v_mfma_f32_16x16x32_bf16 v[68:71], v[132:135], v[248:251], v[68:71]
	v_mfma_f32_16x16x32_bf16 v[72:75], v[136:139], v[248:251], v[72:75]
	v_mfma_f32_16x16x32_bf16 v[76:79], v[140:143], v[248:251], v[76:79]
	v_mfma_f32_16x16x32_bf16 v[80:83], v[144:147], v[248:251], v[80:83]
	v_mfma_f32_16x16x32_bf16 v[84:87], v[132:135], v[148:151], v[84:87]
	v_mfma_f32_16x16x32_bf16 v[88:91], v[136:139], v[148:151], v[88:91]
	v_mfma_f32_16x16x32_bf16 v[92:95], v[140:143], v[148:151], v[92:95]
	v_mfma_f32_16x16x32_bf16 v[96:99], v[144:147], v[148:151], v[96:99]
	s_nop 0
	s_waitcnt vmcnt(0) lgkmcnt(0)
	s_barrier
	s_cmp_lt_u32 s0, 15
	s_cbranch_scc0 .Lg16_nd0_g0a
	s_mov_b32 s3, s44
	s_mov_b32 m0, s3
	s_add_u32 s3, s3, 0x400
	global_load_lds_dwordx4 v220, s[58:59]
	s_mov_b32 m0, s3
	s_add_u32 s3, s3, 0x400
	global_load_lds_dwordx4 v220, s[60:61]
	s_mov_b32 m0, s3
	s_add_u32 s3, s3, 0x400
	global_load_lds_dwordx4 v220, s[62:63]
	s_mov_b32 m0, s3
	s_add_u32 s3, s3, 0x400
	global_load_lds_dwordx4 v220, s[64:65]
	s_mov_b32 m0, s3
	s_add_u32 s3, s3, 0x400
	global_load_lds_dwordx4 v220, s[68:69]
	s_mov_b32 m0, s3
	s_nop 0
	global_load_lds_dwordx4 v220, vcc
	v_add_u32_e32 v220, 64, v220
.Lg16_nd0_g0a:
	ds_read_b128 v[224:227], v219
	ds_read_b128 v[228:231], v219 offset:1024
	ds_read_b128 v[232:235], v219 offset:2048
	ds_read_b128 v[236:239], v219 offset:3072
	ds_read_b128 v[240:243], v218
	ds_read_b128 v[244:247], v218 offset:1024
	ds_read_b128 v[248:251], v218 offset:2048
	ds_read_b128 v[148:151], v218 offset:3072
	s_nop 0
	v_mfma_f32_16x16x32_bf16 v[36:39], v[132:135], v[152:155], v[36:39]
	v_mfma_f32_16x16x32_bf16 v[40:43], v[136:139], v[152:155], v[40:43]
	v_mfma_f32_16x16x32_bf16 v[44:47], v[140:143], v[152:155], v[44:47]
	v_mfma_f32_16x16x32_bf16 v[48:51], v[144:147], v[152:155], v[48:51]
	v_mfma_f32_16x16x32_bf16 v[52:55], v[132:135], v[164:167], v[52:55]
	v_mfma_f32_16x16x32_bf16 v[56:59], v[136:139], v[164:167], v[56:59]
	v_mfma_f32_16x16x32_bf16 v[60:63], v[140:143], v[164:167], v[60:63]
	v_mfma_f32_16x16x32_bf16 v[64:67], v[144:147], v[164:167], v[64:67]
	v_mfma_f32_16x16x32_bf16 v[4:7], v[132:135], v[168:171], v[4:7]
	v_mfma_f32_16x16x32_bf16 v[8:11], v[136:139], v[168:171], v[8:11]
	v_mfma_f32_16x16x32_bf16 v[12:15], v[140:143], v[168:171], v[12:15]
	v_mfma_f32_16x16x32_bf16 v[16:19], v[144:147], v[168:171], v[16:19]
	v_mfma_f32_16x16x32_bf16 v[20:23], v[132:135], v[212:215], v[20:23]
	v_mfma_f32_16x16x32_bf16 v[24:27], v[136:139], v[212:215], v[24:27]
	v_mfma_f32_16x16x32_bf16 v[28:31], v[140:143], v[212:215], v[28:31]
	v_mfma_f32_16x16x32_bf16 v[32:35], v[144:147], v[212:215], v[32:35]
	s_nop 0
	ds_read_b128 v[152:155], v218 offset:4096
	ds_read_b128 v[164:167], v218 offset:5120
	ds_read_b128 v[168:171], v218 offset:6144
	ds_read_b128 v[212:215], v218 offset:7168
	s_nop 0
	s_waitcnt lgkmcnt(4)
	v_mfma_f32_16x16x32_bf16 v[100:103], v[224:227], v[240:243], v[100:103]
	v_mfma_f32_16x16x32_bf16 v[104:107], v[228:231], v[240:243], v[104:107]
	v_mfma_f32_16x16x32_bf16 v[108:111], v[232:235], v[240:243], v[108:111]
	v_mfma_f32_16x16x32_bf16 v[112:115], v[236:239], v[240:243], v[112:115]
	v_mfma_f32_16x16x32_bf16 v[116:119], v[224:227], v[244:247], v[116:119]
	v_mfma_f32_16x16x32_bf16 v[120:123], v[228:231], v[244:247], v[120:123]
	v_mfma_f32_16x16x32_bf16 v[124:127], v[232:235], v[244:247], v[124:127]
	v_mfma_f32_16x16x32_bf16 v[128:131], v[236:239], v[244:247], v[128:131]
	v_mfma_f32_16x16x32_bf16 v[68:71], v[224:227], v[248:251], v[68:71]
	v_mfma_f32_16x16x32_bf16 v[72:75], v[228:231], v[248:251], v[72:75]
	v_mfma_f32_16x16x32_bf16 v[76:79], v[232:235], v[248:251], v[76:79]
	v_mfma_f32_16x16x32_bf16 v[80:83], v[236:239], v[248:251], v[80:83]
	v_mfma_f32_16x16x32_bf16 v[84:87], v[224:227], v[148:151], v[84:87]
	v_mfma_f32_16x16x32_bf16 v[88:91], v[228:231], v[148:151], v[88:91]
	v_mfma_f32_16x16x32_bf16 v[92:95], v[232:235], v[148:151], v[92:95]
	v_mfma_f32_16x16x32_bf16 v[96:99], v[236:239], v[148:151], v[96:99]
	s_nop 0
	s_waitcnt vmcnt(0) lgkmcnt(0)
	s_barrier
	s_cmp_lt_u32 s0, 15
	s_cbranch_scc0 .Lg16_nd1_g0a
	s_add_u32 s3, s44, 0x6000
	s_mov_b32 m0, s3
	s_add_u32 s3, s3, 0x400
	global_load_lds_dwordx4 v220, s[58:59]
	s_mov_b32 m0, s3
	s_add_u32 s3, s3, 0x400
	global_load_lds_dwordx4 v220, s[60:61]
	s_mov_b32 m0, s3
	s_add_u32 s3, s3, 0x400
	global_load_lds_dwordx4 v220, s[62:63]
	s_mov_b32 m0, s3
	s_add_u32 s3, s3, 0x400
	global_load_lds_dwordx4 v220, s[64:65]
	s_mov_b32 m0, s3
	s_add_u32 s3, s3, 0x400
	global_load_lds_dwordx4 v220, s[68:69]
	s_mov_b32 m0, s3
	s_nop 0
	global_load_lds_dwordx4 v220, vcc
	v_add_u32_e32 v220, 64, v220
	ds_read_b128 v[132:135], v217
	ds_read_b128 v[136:139], v217 offset:1024
	ds_read_b128 v[140:143], v217 offset:2048
	ds_read_b128 v[144:147], v217 offset:3072
	ds_read_b128 v[240:243], v216
	ds_read_b128 v[244:247], v216 offset:1024
	ds_read_b128 v[248:251], v216 offset:2048
	ds_read_b128 v[148:151], v216 offset:3072
.Lg16_nd1_g0a:
	s_nop 0
	v_mfma_f32_16x16x32_bf16 v[36:39], v[224:227], v[152:155], v[36:39]
	v_mfma_f32_16x16x32_bf16 v[40:43], v[228:231], v[152:155], v[40:43]
	v_mfma_f32_16x16x32_bf16 v[44:47], v[232:235], v[152:155], v[44:47]
	v_mfma_f32_16x16x32_bf16 v[48:51], v[236:239], v[152:155], v[48:51]
	v_mfma_f32_16x16x32_bf16 v[52:55], v[224:227], v[164:167], v[52:55]
	v_mfma_f32_16x16x32_bf16 v[56:59], v[228:231], v[164:167], v[56:59]
	v_mfma_f32_16x16x32_bf16 v[60:63], v[232:235], v[164:167], v[60:63]
	v_mfma_f32_16x16x32_bf16 v[64:67], v[236:239], v[164:167], v[64:67]
	v_mfma_f32_16x16x32_bf16 v[4:7], v[224:227], v[168:171], v[4:7]
	v_mfma_f32_16x16x32_bf16 v[8:11], v[228:231], v[168:171], v[8:11]
	v_mfma_f32_16x16x32_bf16 v[12:15], v[232:235], v[168:171], v[12:15]
	v_mfma_f32_16x16x32_bf16 v[16:19], v[236:239], v[168:171], v[16:19]
	v_mfma_f32_16x16x32_bf16 v[20:23], v[224:227], v[212:215], v[20:23]
	v_mfma_f32_16x16x32_bf16 v[24:27], v[228:231], v[212:215], v[24:27]
	v_mfma_f32_16x16x32_bf16 v[28:31], v[232:235], v[212:215], v[28:31]
	v_mfma_f32_16x16x32_bf16 v[32:35], v[236:239], v[212:215], v[32:35]
	s_nop 0
	s_add_u32 s0, s0, 1
	s_cmp_lt_u32 s0, 16
	s_cbranch_scc1 .Lg16_loop_g0a
	s_nop 7
	s_and_b32 s0, s48, -4
	s_cmp_lg_u32 s0, 8
	s_cselect_b64 s[0:1], -1, 0
	s_add_i32 s2, s46, 0xfffffe00
	s_nop 5
	s_barrier
	s_cmp_lt_i32 s47, -8
	s_cselect_b32 s2, s46, s2
	v_or_b32_e32 v134, s2, v206
	v_and_b32_e32 v145, 63, v160
	v_lshrrev_b32_e32 v146, 6, v160
	v_and_b32_e32 v147, 15, v145
	v_lshrrev_b32_e32 v145, 4, v145
	v_mul_u32_u24_e32 v147, 0x90, v147
	v_lshl_add_u32 v147, v145, 3, v147
	v_mul_u32_u24_e32 v146, 0x2400, v146
	v_add_u32_e32 v144, v147, v146
	v_cvt_pk_bf16_f32 v136, v100, v101
	v_cvt_pk_bf16_f32 v137, v102, v103
	ds_write_b64 v144, v[136:137]
	v_cvt_pk_bf16_f32 v138, v104, v105
	v_cvt_pk_bf16_f32 v139, v106, v107
	ds_write_b64 v144, v[138:139] offset:32
	v_cvt_pk_bf16_f32 v140, v108, v109
	v_cvt_pk_bf16_f32 v141, v110, v111
	ds_write_b64 v144, v[140:141] offset:64
	v_cvt_pk_bf16_f32 v142, v112, v113
	v_cvt_pk_bf16_f32 v143, v114, v115
	ds_write_b64 v144, v[142:143] offset:96
	v_cvt_pk_bf16_f32 v136, v116, v117
	v_cvt_pk_bf16_f32 v137, v118, v119
	ds_write_b64 v144, v[136:137] offset:2304
	v_cvt_pk_bf16_f32 v138, v120, v121
	v_cvt_pk_bf16_f32 v139, v122, v123
	ds_write_b64 v144, v[138:139] offset:2336
	v_cvt_pk_bf16_f32 v140, v124, v125
	v_cvt_pk_bf16_f32 v141, v126, v127
	ds_write_b64 v144, v[140:141] offset:2368
	v_cvt_pk_bf16_f32 v142, v128, v129
	v_cvt_pk_bf16_f32 v143, v130, v131
	ds_write_b64 v144, v[142:143] offset:2400
	v_cvt_pk_bf16_f32 v136, v68, v69
	v_cvt_pk_bf16_f32 v137, v70, v71
	ds_write_b64 v144, v[136:137] offset:4608
	v_cvt_pk_bf16_f32 v138, v72, v73
	v_cvt_pk_bf16_f32 v139, v74, v75
	ds_write_b64 v144, v[138:139] offset:4640
	v_cvt_pk_bf16_f32 v140, v76, v77
	v_cvt_pk_bf16_f32 v141, v78, v79
	ds_write_b64 v144, v[140:141] offset:4672
	v_cvt_pk_bf16_f32 v142, v80, v81
	v_cvt_pk_bf16_f32 v143, v82, v83
	ds_write_b64 v144, v[142:143] offset:4704
	v_cvt_pk_bf16_f32 v136, v84, v85
	v_cvt_pk_bf16_f32 v137, v86, v87
	ds_write_b64 v144, v[136:137] offset:6912
	v_cvt_pk_bf16_f32 v138, v88, v89
	v_cvt_pk_bf16_f32 v139, v90, v91
	ds_write_b64 v144, v[138:139] offset:6944
	v_cvt_pk_bf16_f32 v140, v92, v93
	v_cvt_pk_bf16_f32 v141, v94, v95
	ds_write_b64 v144, v[140:141] offset:6976
	v_cvt_pk_bf16_f32 v142, v96, v97
	v_cvt_pk_bf16_f32 v143, v98, v99
	ds_write_b64 v144, v[142:143] offset:7008
	s_waitcnt lgkmcnt(0)
	v_ashrrev_i32_e32 v135, 31, v134
	v_add_u32_e32 v132, s49, v161
	s_mov_b64 s[2:3], -1
	s_and_b64 vcc, exec, s[0:1]
	v_lshlrev_b64 v[82:83], 1, v[134:135]
	s_cbranch_vccz .LBB0_244
	ds_read_b128 v[68:71], v210
	v_readlane_b32 s4, v254, 62
	v_readlane_b32 s18, v255, 12
	v_readlane_b32 s19, v255, 13
	v_or_b32_e32 v74, v132, v172
	v_readlane_b32 s5, v254, 63
	v_mov_b64_e32 v[72:73], s[18:19]
	v_mad_i64_i32 v[74:75], s[2:3], v74, s51, v[72:73]
	v_lshl_add_u64 v[74:75], v[74:75], 0, v[82:83]
	s_waitcnt lgkmcnt(0)
	global_store_dwordx4 v[74:75], v[68:71], off
	ds_read_b128 v[68:71], v210 offset:1152
	v_or_b32_e32 v74, v132, v176
	v_mad_i64_i32 v[74:75], s[2:3], v74, s51, v[72:73]
	v_lshl_add_u64 v[74:75], v[74:75], 0, v[82:83]
	s_waitcnt lgkmcnt(0)
	global_store_dwordx4 v[74:75], v[68:71], off
	ds_read_b128 v[68:71], v210 offset:2304
	v_or_b32_e32 v74, v132, v178
	v_mad_i64_i32 v[74:75], s[2:3], v74, s51, v[72:73]
	v_lshl_add_u64 v[74:75], v[74:75], 0, v[82:83]
	s_waitcnt lgkmcnt(0)
	global_store_dwordx4 v[74:75], v[68:71], off
	ds_read_b128 v[68:71], v210 offset:3456
	v_or_b32_e32 v74, v132, v179
	v_mad_i64_i32 v[74:75], s[2:3], v74, s51, v[72:73]
	v_lshl_add_u64 v[74:75], v[74:75], 0, v[82:83]
	s_waitcnt lgkmcnt(0)
	global_store_dwordx4 v[74:75], v[68:71], off
	ds_read_b128 v[68:71], v210 offset:4608
	v_or_b32_e32 v74, v132, v180
	v_mad_i64_i32 v[74:75], s[2:3], v74, s51, v[72:73]
	v_lshl_add_u64 v[74:75], v[74:75], 0, v[82:83]
	s_waitcnt lgkmcnt(0)
	global_store_dwordx4 v[74:75], v[68:71], off
	ds_read_b128 v[68:71], v210 offset:5760
	v_or_b32_e32 v74, v132, v181
	v_mad_i64_i32 v[74:75], s[2:3], v74, s51, v[72:73]
	v_lshl_add_u64 v[74:75], v[74:75], 0, v[82:83]
	s_waitcnt lgkmcnt(0)
	global_store_dwordx4 v[74:75], v[68:71], off
	ds_read_b128 v[68:71], v210 offset:6912
	v_or_b32_e32 v74, v132, v202
	v_mad_i64_i32 v[74:75], s[2:3], v74, s51, v[72:73]
	v_lshl_add_u64 v[74:75], v[74:75], 0, v[82:83]
	s_waitcnt lgkmcnt(0)
	global_store_dwordx4 v[74:75], v[68:71], off
	ds_read_b128 v[68:71], v210 offset:8064
	v_or_b32_e32 v74, v132, v203
	v_mad_i64_i32 v[72:73], s[2:3], v74, s51, v[72:73]
	v_lshl_add_u64 v[72:73], v[72:73], 0, v[82:83]
	s_mov_b64 s[2:3], 0
	v_readlane_b32 s6, v255, 0
	v_readlane_b32 s7, v255, 1
	v_readlane_b32 s8, v255, 2
	v_readlane_b32 s9, v255, 3
	v_readlane_b32 s10, v255, 4
	v_readlane_b32 s11, v255, 5
	v_readlane_b32 s12, v255, 6
	v_readlane_b32 s13, v255, 7
	v_readlane_b32 s14, v255, 8
	v_readlane_b32 s15, v255, 9
	v_readlane_b32 s16, v255, 10
	v_readlane_b32 s17, v255, 11
	s_waitcnt lgkmcnt(0)
	global_store_dwordx4 v[72:73], v[68:71], off

.Lg16_loop_g1:
	ds_read_b128 v[152:155], v216 offset:4096
	ds_read_b128 v[164:167], v216 offset:5120
	ds_read_b128 v[168:171], v216 offset:6144
	ds_read_b128 v[212:215], v216 offset:7168
	s_nop 0
	s_waitcnt lgkmcnt(4)
	v_mfma_f32_16x16x32_bf16 v[100:103], v[132:135], v[240:243], v[100:103]
	v_mfma_f32_16x16x32_bf16 v[104:107], v[136:139], v[240:243], v[104:107]
	v_mfma_f32_16x16x32_bf16 v[108:111], v[140:143], v[240:243], v[108:111]
	v_mfma_f32_16x16x32_bf16 v[112:115], v[144:147], v[240:243], v[112:115]
	v_mfma_f32_16x16x32_bf16 v[116:119], v[132:135], v[244:247], v[116:119]
	v_mfma_f32_16x16x32_bf16 v[120:123], v[136:139], v[244:247], v[120:123]
	v_mfma_f32_16x16x32_bf16 v[124:127], v[140:143], v[244:247], v[124:127]
	v_mfma_f32_16x16x32_bf16 v[128:131], v[144:147], v[244:247], v[128:131]
	v_mfma_f32_16x16x32_bf16 v[68:71], v[132:135], v[248:251], v[68:71]
	v_mfma_f32_16x16x32_bf16 v[72:75], v[136:139], v[248:251], v[72:75]
	v_mfma_f32_16x16x32_bf16 v[76:79], v[140:143], v[248:251], v[76:79]
	v_mfma_f32_16x16x32_bf16 v[80:83], v[144:147], v[248:251], v[80:83]
	v_mfma_f32_16x16x32_bf16 v[84:87], v[132:135], v[148:151], v[84:87]
	v_mfma_f32_16x16x32_bf16 v[88:91], v[136:139], v[148:151], v[88:91]
	v_mfma_f32_16x16x32_bf16 v[92:95], v[140:143], v[148:151], v[92:95]
	v_mfma_f32_16x16x32_bf16 v[96:99], v[144:147], v[148:151], v[96:99]
	s_nop 0
	s_waitcnt vmcnt(0) lgkmcnt(0)
	s_barrier
	s_cmp_lt_u32 s40, 15
	s_cbranch_scc0 .Lg16_nd0_g1
	s_mov_b32 s41, s31
	s_mov_b32 m0, s41
	s_add_u32 s41, s41, 0x400
	global_load_lds_dwordx4 v220, s[58:59]
	s_mov_b32 m0, s41
	s_add_u32 s41, s41, 0x400
	global_load_lds_dwordx4 v220, s[60:61]
	s_mov_b32 m0, s41
	s_add_u32 s41, s41, 0x400
	global_load_lds_dwordx4 v220, s[62:63]
	s_mov_b32 m0, s41
	s_add_u32 s41, s41, 0x400
	global_load_lds_dwordx4 v220, s[64:65]
	s_mov_b32 m0, s41
	s_add_u32 s41, s41, 0x400
	global_load_lds_dwordx4 v220, s[68:69]
	s_mov_b32 m0, s41
	s_nop 0
	global_load_lds_dwordx4 v220, vcc
	v_add_u32_e32 v220, 64, v220
.Lg16_nd0_g1:
	ds_read_b128 v[224:227], v219
	ds_read_b128 v[228:231], v219 offset:1024
	ds_read_b128 v[232:235], v219 offset:2048
	ds_read_b128 v[236:239], v219 offset:3072
	ds_read_b128 v[240:243], v218
	ds_read_b128 v[244:247], v218 offset:1024
	ds_read_b128 v[248:251], v218 offset:2048
	ds_read_b128 v[148:151], v218 offset:3072
	s_nop 0
	v_mfma_f32_16x16x32_bf16 v[36:39], v[132:135], v[152:155], v[36:39]
	v_mfma_f32_16x16x32_bf16 v[40:43], v[136:139], v[152:155], v[40:43]
	v_mfma_f32_16x16x32_bf16 v[44:47], v[140:143], v[152:155], v[44:47]
	v_mfma_f32_16x16x32_bf16 v[48:51], v[144:147], v[152:155], v[48:51]
	v_mfma_f32_16x16x32_bf16 v[52:55], v[132:135], v[164:167], v[52:55]
	v_mfma_f32_16x16x32_bf16 v[56:59], v[136:139], v[164:167], v[56:59]
	v_mfma_f32_16x16x32_bf16 v[60:63], v[140:143], v[164:167], v[60:63]
	v_mfma_f32_16x16x32_bf16 v[64:67], v[144:147], v[164:167], v[64:67]
	v_mfma_f32_16x16x32_bf16 v[4:7], v[132:135], v[168:171], v[4:7]
	v_mfma_f32_16x16x32_bf16 v[8:11], v[136:139], v[168:171], v[8:11]
	v_mfma_f32_16x16x32_bf16 v[12:15], v[140:143], v[168:171], v[12:15]
	v_mfma_f32_16x16x32_bf16 v[16:19], v[144:147], v[168:171], v[16:19]
	v_mfma_f32_16x16x32_bf16 v[20:23], v[132:135], v[212:215], v[20:23]
	v_mfma_f32_16x16x32_bf16 v[24:27], v[136:139], v[212:215], v[24:27]
	v_mfma_f32_16x16x32_bf16 v[28:31], v[140:143], v[212:215], v[28:31]
	v_mfma_f32_16x16x32_bf16 v[32:35], v[144:147], v[212:215], v[32:35]
	s_nop 0
	ds_read_b128 v[152:155], v218 offset:4096
	ds_read_b128 v[164:167], v218 offset:5120
	ds_read_b128 v[168:171], v218 offset:6144
	ds_read_b128 v[212:215], v218 offset:7168
	s_nop 0
	s_waitcnt lgkmcnt(4)
	v_mfma_f32_16x16x32_bf16 v[100:103], v[224:227], v[240:243], v[100:103]
	v_mfma_f32_16x16x32_bf16 v[104:107], v[228:231], v[240:243], v[104:107]
	v_mfma_f32_16x16x32_bf16 v[108:111], v[232:235], v[240:243], v[108:111]
	v_mfma_f32_16x16x32_bf16 v[112:115], v[236:239], v[240:243], v[112:115]
	v_mfma_f32_16x16x32_bf16 v[116:119], v[224:227], v[244:247], v[116:119]
	v_mfma_f32_16x16x32_bf16 v[120:123], v[228:231], v[244:247], v[120:123]
	v_mfma_f32_16x16x32_bf16 v[124:127], v[232:235], v[244:247], v[124:127]
	v_mfma_f32_16x16x32_bf16 v[128:131], v[236:239], v[244:247], v[128:131]
	v_mfma_f32_16x16x32_bf16 v[68:71], v[224:227], v[248:251], v[68:71]
	v_mfma_f32_16x16x32_bf16 v[72:75], v[228:231], v[248:251], v[72:75]
	v_mfma_f32_16x16x32_bf16 v[76:79], v[232:235], v[248:251], v[76:79]
	v_mfma_f32_16x16x32_bf16 v[80:83], v[236:239], v[248:251], v[80:83]
	v_mfma_f32_16x16x32_bf16 v[84:87], v[224:227], v[148:151], v[84:87]
	v_mfma_f32_16x16x32_bf16 v[88:91], v[228:231], v[148:151], v[88:91]
	v_mfma_f32_16x16x32_bf16 v[92:95], v[232:235], v[148:151], v[92:95]
	v_mfma_f32_16x16x32_bf16 v[96:99], v[236:239], v[148:151], v[96:99]
	s_nop 0
	s_waitcnt vmcnt(0) lgkmcnt(0)
	s_barrier
	s_cmp_lt_u32 s40, 15
	s_cbranch_scc0 .Lg16_nd1_g1
	s_add_u32 s41, s31, 0x6000
	s_mov_b32 m0, s41
	s_add_u32 s41, s41, 0x400
	global_load_lds_dwordx4 v220, s[58:59]
	s_mov_b32 m0, s41
	s_add_u32 s41, s41, 0x400
	global_load_lds_dwordx4 v220, s[60:61]
	s_mov_b32 m0, s41
	s_add_u32 s41, s41, 0x400
	global_load_lds_dwordx4 v220, s[62:63]
	s_mov_b32 m0, s41
	s_add_u32 s41, s41, 0x400
	global_load_lds_dwordx4 v220, s[64:65]
	s_mov_b32 m0, s41
	s_add_u32 s41, s41, 0x400
	global_load_lds_dwordx4 v220, s[68:69]
	s_mov_b32 m0, s41
	s_nop 0
	global_load_lds_dwordx4 v220, vcc
	v_add_u32_e32 v220, 64, v220
	ds_read_b128 v[132:135], v217
	ds_read_b128 v[136:139], v217 offset:1024
	ds_read_b128 v[140:143], v217 offset:2048
	ds_read_b128 v[144:147], v217 offset:3072
	ds_read_b128 v[240:243], v216
	ds_read_b128 v[244:247], v216 offset:1024
	ds_read_b128 v[248:251], v216 offset:2048
	ds_read_b128 v[148:151], v216 offset:3072
.Lg16_nd1_g1:
	s_nop 0
	v_mfma_f32_16x16x32_bf16 v[36:39], v[224:227], v[152:155], v[36:39]
	v_mfma_f32_16x16x32_bf16 v[40:43], v[228:231], v[152:155], v[40:43]
	v_mfma_f32_16x16x32_bf16 v[44:47], v[232:235], v[152:155], v[44:47]
	v_mfma_f32_16x16x32_bf16 v[48:51], v[236:239], v[152:155], v[48:51]
	v_mfma_f32_16x16x32_bf16 v[52:55], v[224:227], v[164:167], v[52:55]
	v_mfma_f32_16x16x32_bf16 v[56:59], v[228:231], v[164:167], v[56:59]
	v_mfma_f32_16x16x32_bf16 v[60:63], v[232:235], v[164:167], v[60:63]
	v_mfma_f32_16x16x32_bf16 v[64:67], v[236:239], v[164:167], v[64:67]
	v_mfma_f32_16x16x32_bf16 v[4:7], v[224:227], v[168:171], v[4:7]
	v_mfma_f32_16x16x32_bf16 v[8:11], v[228:231], v[168:171], v[8:11]
	v_mfma_f32_16x16x32_bf16 v[12:15], v[232:235], v[168:171], v[12:15]
	v_mfma_f32_16x16x32_bf16 v[16:19], v[236:239], v[168:171], v[16:19]
	v_mfma_f32_16x16x32_bf16 v[20:23], v[224:227], v[212:215], v[20:23]
	v_mfma_f32_16x16x32_bf16 v[24:27], v[228:231], v[212:215], v[24:27]
	v_mfma_f32_16x16x32_bf16 v[28:31], v[232:235], v[212:215], v[28:31]
	v_mfma_f32_16x16x32_bf16 v[32:35], v[236:239], v[212:215], v[32:35]
	s_nop 0
	s_add_u32 s40, s40, 1
	s_cmp_lt_u32 s40, 16
	s_cbranch_scc1 .Lg16_loop_g1
	s_nop 7
	v_add_u32_e32 v132, s39, v161
	v_ashrrev_i32_e32 v133, 31, v132
	v_lshlrev_b64 v[132:133], 10, v[132:133]
	s_ashr_i32 s39, s38, 31
	v_lshl_add_u64 v[132:133], v[132:133], 0, s[38:39]
	v_or_b32_e32 v132, v132, v0
	v_lshlrev_b64 v[132:133], 2, v[132:133]
	s_barrier
	v_lshl_add_u64 v[154:155], s[0:1], 0, v[132:133]
	v_and_b32_e32 v217, 63, v160
	v_lshrrev_b32_e32 v218, 6, v160
	v_and_b32_e32 v219, 15, v217
	v_lshrrev_b32_e32 v217, 4, v217
	v_mul_u32_u24_e32 v219, 0x110, v219
	v_lshl_add_u32 v219, v217, 4, v219
	v_mul_u32_u24_e32 v218, 0x2200, v218
	v_add_u32_e32 v216, v219, v218
	ds_write_b128 v216, v[100:103]
	ds_write_b128 v216, v[104:107] offset:64
	ds_write_b128 v216, v[108:111] offset:128
	ds_write_b128 v216, v[112:115] offset:192
	ds_write_b128 v216, v[116:119] offset:4352
	ds_write_b128 v216, v[120:123] offset:4416
	ds_write_b128 v216, v[124:127] offset:4480
	ds_write_b128 v216, v[128:131] offset:4544
	global_load_dwordx4 v[164:167], v[154:155], off
	s_movk_i32 s2, 0x4000
	v_add_co_u32_e32 v100, vcc, s2, v154
	s_mov_b32 s57, 0x8000
	s_nop 0
	v_addc_co_u32_e32 v101, vcc, 0, v155, vcc
	global_load_dwordx4 v[168:171], v[100:101], off
	v_add_co_u32_e32 v100, vcc, s57, v154
	s_mov_b32 s3, 0xc000
	s_nop 0
	v_addc_co_u32_e32 v101, vcc, 0, v155, vcc
	global_load_dwordx4 v[202:205], v[100:101], off
	v_add_co_u32_e32 v100, vcc, s3, v154
	s_mov_b32 s20, 0x10000
	s_nop 0
	v_addc_co_u32_e32 v101, vcc, 0, v155, vcc
	global_load_dwordx4 v[148:151], v[100:101], off
	v_add_co_u32_e32 v100, vcc, s20, v154
	s_mov_b32 s21, 0x14000
	s_nop 0
	v_addc_co_u32_e32 v101, vcc, 0, v155, vcc
	global_load_dwordx4 v[144:147], v[100:101], off
	v_add_co_u32_e32 v100, vcc, s21, v154
	s_mov_b32 s30, 0x18000
	s_nop 0
	v_addc_co_u32_e32 v101, vcc, 0, v155, vcc
	global_load_dwordx4 v[140:143], v[100:101], off
	v_add_co_u32_e32 v100, vcc, s30, v154
	s_mov_b32 s31, 0x1c000
	s_nop 0
	v_addc_co_u32_e32 v101, vcc, 0, v155, vcc
	global_load_dwordx4 v[136:139], v[100:101], off
	v_readlane_b32 s4, v254, 62
	v_add_co_u32_e32 v100, vcc, s31, v154
	v_readlane_b32 s10, v255, 4
	v_readlane_b32 s11, v255, 5
	v_addc_co_u32_e32 v101, vcc, 0, v155, vcc
	s_nop 0
	v_lshl_add_u64 v[152:153], s[10:11], 0, v[132:133]
	global_load_dwordx4 v[132:135], v[100:101], off
	s_mov_b32 s38, 0x20000
	v_add_co_u32_e32 v100, vcc, s38, v154
	s_mov_b32 s39, 0x24000
	s_nop 0
	v_addc_co_u32_e32 v101, vcc, 0, v155, vcc
	global_load_dwordx4 v[128:131], v[100:101], off
	v_add_co_u32_e32 v100, vcc, s39, v154
	s_mov_b32 s40, 0x28000
	s_nop 0
	v_addc_co_u32_e32 v101, vcc, 0, v155, vcc
	global_load_dwordx4 v[124:127], v[100:101], off
	v_add_co_u32_e32 v100, vcc, s40, v154
	s_mov_b32 s41, 0x2c000
	s_nop 0
	v_addc_co_u32_e32 v101, vcc, 0, v155, vcc
	global_load_dwordx4 v[120:123], v[100:101], off
	v_add_co_u32_e32 v100, vcc, s41, v154
	s_mov_b32 s42, 0x30000
	s_nop 0
	v_addc_co_u32_e32 v101, vcc, 0, v155, vcc
	global_load_dwordx4 v[116:119], v[100:101], off
	v_add_co_u32_e32 v100, vcc, s42, v154
	s_mov_b32 s43, 0x34000
	s_nop 0
	v_addc_co_u32_e32 v101, vcc, 0, v155, vcc
	global_load_dwordx4 v[112:115], v[100:101], off
	v_add_co_u32_e32 v100, vcc, s43, v154
	s_mov_b32 s44, 0x38000
	s_nop 0
	v_addc_co_u32_e32 v101, vcc, 0, v155, vcc
	global_load_dwordx4 v[108:111], v[100:101], off
	v_add_co_u32_e32 v100, vcc, s44, v154
	s_mov_b32 s45, 0x3c000
	s_nop 0
	v_addc_co_u32_e32 v101, vcc, 0, v155, vcc
	global_load_dwordx4 v[104:107], v[100:101], off
	v_add_co_u32_e32 v100, vcc, s45, v154
	s_mov_b32 s58, 0x50000
	s_nop 0
	v_addc_co_u32_e32 v101, vcc, 0, v155, vcc
	global_load_dwordx4 v[100:103], v[100:101], off
	s_waitcnt lgkmcnt(0)
	ds_read_b128 v[206:209], v176
	s_mov_b32 s59, 0x58000
	s_mov_b32 s60, 0x5c000
	s_add_i32 s24, s24, s48
	s_cmpk_gt_i32 s24, 0x7f
	s_waitcnt vmcnt(15) lgkmcnt(0)
	v_pk_add_f32 v[164:165], v[164:165], v[206:207]
	v_pk_add_f32 v[166:167], v[166:167], v[208:209]
	global_store_dwordx4 v[152:153], v[164:167], off
	ds_read_b128 v[164:167], v176 offset:1088
	v_readlane_b32 s5, v254, 63
	v_readlane_b32 s6, v255, 0
	v_readlane_b32 s7, v255, 1
	v_readlane_b32 s8, v255, 2
	s_waitcnt vmcnt(15) lgkmcnt(0)
	v_pk_add_f32 v[164:165], v[168:169], v[164:165]
	v_add_co_u32_e32 v168, vcc, s2, v152
	v_pk_add_f32 v[166:167], v[170:171], v[166:167]
	s_nop 0
	v_addc_co_u32_e32 v169, vcc, 0, v153, vcc
	global_store_dwordx4 v[168:169], v[164:167], off
	ds_read_b128 v[164:167], v176 offset:2176
	v_add_co_u32_e32 v168, vcc, s57, v152
	s_mov_b32 s2, 0x7c000
	s_nop 0
	v_addc_co_u32_e32 v169, vcc, 0, v153, vcc
	s_waitcnt vmcnt(15) lgkmcnt(0)
	v_pk_add_f32 v[164:165], v[202:203], v[164:165]
	v_pk_add_f32 v[166:167], v[204:205], v[166:167]
	global_store_dwordx4 v[168:169], v[164:167], off
	ds_read_b128 v[164:167], v176 offset:3264
	v_readlane_b32 s9, v255, 3
	v_readlane_b32 s12, v255, 6
	v_readlane_b32 s13, v255, 7
	v_readlane_b32 s14, v255, 8
	s_waitcnt vmcnt(15) lgkmcnt(0)
	v_pk_add_f32 v[148:149], v[148:149], v[164:165]
	v_add_co_u32_e32 v164, vcc, s3, v152
	v_pk_add_f32 v[150:151], v[150:151], v[166:167]
	s_nop 0
	v_addc_co_u32_e32 v165, vcc, 0, v153, vcc
	global_store_dwordx4 v[164:165], v[148:151], off
	ds_read_b128 v[148:151], v176 offset:4352
	s_mov_b32 s3, 0x54000
	v_readlane_b32 s15, v255, 9
	v_readlane_b32 s16, v255, 10
	v_readlane_b32 s17, v255, 11
	s_waitcnt vmcnt(15) lgkmcnt(0)
	v_pk_add_f32 v[144:145], v[144:145], v[148:149]
	v_add_co_u32_e32 v148, vcc, s20, v152
	v_pk_add_f32 v[146:147], v[146:147], v[150:151]
	s_nop 0
	v_addc_co_u32_e32 v149, vcc, 0, v153, vcc
	global_store_dwordx4 v[148:149], v[144:147], off
	ds_read_b128 v[144:147], v176 offset:5440
	s_mov_b32 s20, 0x40000
	v_readlane_b32 s18, v255, 12
	v_readlane_b32 s19, v255, 13
	s_waitcnt vmcnt(15) lgkmcnt(0)
	v_pk_add_f32 v[140:141], v[140:141], v[144:145]
	v_add_co_u32_e32 v144, vcc, s21, v152
	v_pk_add_f32 v[142:143], v[142:143], v[146:147]
	s_nop 0
	v_addc_co_u32_e32 v145, vcc, 0, v153, vcc
	global_store_dwordx4 v[144:145], v[140:143], off
	ds_read_b128 v[140:143], v176 offset:6528
	s_mov_b32 s21, 0x44000
	s_waitcnt vmcnt(15) lgkmcnt(0)
	v_pk_add_f32 v[136:137], v[136:137], v[140:141]
	v_add_co_u32_e32 v140, vcc, s30, v152
	v_pk_add_f32 v[138:139], v[138:139], v[142:143]
	s_nop 0
	v_addc_co_u32_e32 v141, vcc, 0, v153, vcc
	global_store_dwordx4 v[140:141], v[136:139], off
	ds_read_b128 v[136:139], v176 offset:7616
	s_mov_b32 s30, 0x48000
	s_waitcnt vmcnt(15) lgkmcnt(0)
	v_pk_add_f32 v[132:133], v[132:133], v[136:137]
	v_add_co_u32_e32 v136, vcc, s31, v152
	v_pk_add_f32 v[134:135], v[134:135], v[138:139]
	s_nop 0
	v_addc_co_u32_e32 v137, vcc, 0, v153, vcc
	global_store_dwordx4 v[136:137], v[132:135], off
	s_waitcnt lgkmcnt(0)
	ds_write_b128 v216, v[68:71]
	ds_write_b128 v216, v[72:75] offset:64
	ds_write_b128 v216, v[76:79] offset:128
	ds_write_b128 v216, v[80:83] offset:192
	ds_write_b128 v216, v[84:87] offset:4352
	ds_write_b128 v216, v[88:91] offset:4416
	ds_write_b128 v216, v[92:95] offset:4480
	ds_write_b128 v216, v[96:99] offset:4544
	v_add_co_u32_e32 v68, vcc, s20, v154
	s_mov_b32 s31, 0x4c000
	s_nop 0
	v_addc_co_u32_e32 v69, vcc, 0, v155, vcc
	global_load_dwordx4 v[96:99], v[68:69], off
	v_add_co_u32_e32 v68, vcc, s21, v154
	s_nop 1
	v_addc_co_u32_e32 v69, vcc, 0, v155, vcc
	global_load_dwordx4 v[92:95], v[68:69], off
	v_add_co_u32_e32 v68, vcc, s30, v154
	s_nop 1
	v_addc_co_u32_e32 v69, vcc, 0, v155, vcc
	global_load_dwordx4 v[88:91], v[68:69], off
	v_add_co_u32_e32 v68, vcc, s31, v154
	s_nop 1
	v_addc_co_u32_e32 v69, vcc, 0, v155, vcc
	global_load_dwordx4 v[84:87], v[68:69], off
	v_add_co_u32_e32 v68, vcc, s58, v154
	s_nop 1
	v_addc_co_u32_e32 v69, vcc, 0, v155, vcc
	global_load_dwordx4 v[80:83], v[68:69], off
	v_add_co_u32_e32 v68, vcc, s3, v154
	s_nop 1
	v_addc_co_u32_e32 v69, vcc, 0, v155, vcc
	global_load_dwordx4 v[76:79], v[68:69], off
	v_add_co_u32_e32 v68, vcc, s59, v154
	s_nop 1
	v_addc_co_u32_e32 v69, vcc, 0, v155, vcc
	global_load_dwordx4 v[72:75], v[68:69], off
	v_add_co_u32_e32 v68, vcc, s60, v154
	s_nop 1
	v_addc_co_u32_e32 v69, vcc, 0, v155, vcc
	global_load_dwordx4 v[68:71], v[68:69], off
	s_waitcnt lgkmcnt(0)
	ds_read_b128 v[132:135], v176
	s_waitcnt vmcnt(23) lgkmcnt(0)
	v_pk_add_f32 v[128:129], v[128:129], v[132:133]
	v_add_co_u32_e32 v132, vcc, s38, v152
	v_pk_add_f32 v[130:131], v[130:131], v[134:135]
	s_nop 0
	v_addc_co_u32_e32 v133, vcc, 0, v153, vcc
	global_store_dwordx4 v[132:133], v[128:131], off
	ds_read_b128 v[128:131], v176 offset:1088
	s_mov_b32 s38, 0x60000
	s_waitcnt vmcnt(23) lgkmcnt(0)
	v_pk_add_f32 v[124:125], v[124:125], v[128:129]
	v_add_co_u32_e32 v128, vcc, s39, v152
	v_pk_add_f32 v[126:127], v[126:127], v[130:131]
	s_nop 0
	v_addc_co_u32_e32 v129, vcc, 0, v153, vcc
	global_store_dwordx4 v[128:129], v[124:127], off
	ds_read_b128 v[124:127], v176 offset:2176
	s_mov_b32 s39, 0x64000
	s_waitcnt vmcnt(23) lgkmcnt(0)
	v_pk_add_f32 v[120:121], v[120:121], v[124:125]
	v_add_co_u32_e32 v124, vcc, s40, v152
	v_pk_add_f32 v[122:123], v[122:123], v[126:127]
	s_nop 0
	v_addc_co_u32_e32 v125, vcc, 0, v153, vcc
	global_store_dwordx4 v[124:125], v[120:123], off
	ds_read_b128 v[120:123], v176 offset:3264
	s_mov_b32 s40, 0x68000
	s_waitcnt vmcnt(23) lgkmcnt(0)
	v_pk_add_f32 v[116:117], v[116:117], v[120:121]
	v_add_co_u32_e32 v120, vcc, s41, v152
	v_pk_add_f32 v[118:119], v[118:119], v[122:123]
	s_nop 0
	v_addc_co_u32_e32 v121, vcc, 0, v153, vcc
	global_store_dwordx4 v[120:121], v[116:119], off
	ds_read_b128 v[116:119], v176 offset:4352
	s_mov_b32 s41, 0x6c000
	s_waitcnt vmcnt(23) lgkmcnt(0)
	v_pk_add_f32 v[112:113], v[112:113], v[116:117]
	v_add_co_u32_e32 v116, vcc, s42, v152
	v_pk_add_f32 v[114:115], v[114:115], v[118:119]
	s_nop 0
	v_addc_co_u32_e32 v117, vcc, 0, v153, vcc
	global_store_dwordx4 v[116:117], v[112:115], off
	ds_read_b128 v[112:115], v176 offset:5440
	s_mov_b32 s42, 0x70000
	s_waitcnt vmcnt(23) lgkmcnt(0)
	v_pk_add_f32 v[108:109], v[108:109], v[112:113]
	v_add_co_u32_e32 v112, vcc, s43, v152
	v_pk_add_f32 v[110:111], v[110:111], v[114:115]
	s_nop 0
	v_addc_co_u32_e32 v113, vcc, 0, v153, vcc
	global_store_dwordx4 v[112:113], v[108:111], off
	ds_read_b128 v[108:111], v176 offset:6528
	s_mov_b32 s43, 0x74000
	s_waitcnt vmcnt(23) lgkmcnt(0)
	v_pk_add_f32 v[104:105], v[104:105], v[108:109]
	v_add_co_u32_e32 v108, vcc, s44, v152
	v_pk_add_f32 v[106:107], v[106:107], v[110:111]
	s_nop 0
	v_addc_co_u32_e32 v109, vcc, 0, v153, vcc
	global_store_dwordx4 v[108:109], v[104:107], off
	ds_read_b128 v[104:107], v176 offset:7616
	s_mov_b32 s44, 0x78000
	s_waitcnt vmcnt(23) lgkmcnt(0)
	v_pk_add_f32 v[100:101], v[100:101], v[104:105]
	v_add_co_u32_e32 v104, vcc, s45, v152
	v_pk_add_f32 v[102:103], v[102:103], v[106:107]
	s_nop 0
	v_addc_co_u32_e32 v105, vcc, 0, v153, vcc
	global_store_dwordx4 v[104:105], v[100:103], off
	s_waitcnt lgkmcnt(0)
	ds_write_b128 v216, v[36:39]
	ds_write_b128 v216, v[40:43] offset:64
	ds_write_b128 v216, v[44:47] offset:128
	ds_write_b128 v216, v[48:51] offset:192
	ds_write_b128 v216, v[52:55] offset:4352
	ds_write_b128 v216, v[56:59] offset:4416
	ds_write_b128 v216, v[60:63] offset:4480
	ds_write_b128 v216, v[64:67] offset:4544
	v_add_co_u32_e32 v36, vcc, s38, v154
	s_nop 1
	v_addc_co_u32_e32 v37, vcc, 0, v155, vcc
	global_load_dwordx4 v[64:67], v[36:37], off
	v_add_co_u32_e32 v36, vcc, s39, v154
	s_nop 1
	v_addc_co_u32_e32 v37, vcc, 0, v155, vcc
	global_load_dwordx4 v[60:63], v[36:37], off
	v_add_co_u32_e32 v36, vcc, s40, v154
	s_nop 1
	v_addc_co_u32_e32 v37, vcc, 0, v155, vcc
	global_load_dwordx4 v[56:59], v[36:37], off
	v_add_co_u32_e32 v36, vcc, s41, v154
	s_nop 1
	v_addc_co_u32_e32 v37, vcc, 0, v155, vcc
	global_load_dwordx4 v[52:55], v[36:37], off
	v_add_co_u32_e32 v36, vcc, s42, v154
	s_nop 1
	v_addc_co_u32_e32 v37, vcc, 0, v155, vcc
	global_load_dwordx4 v[48:51], v[36:37], off
	v_add_co_u32_e32 v36, vcc, s43, v154
	s_nop 1
	v_addc_co_u32_e32 v37, vcc, 0, v155, vcc
	global_load_dwordx4 v[44:47], v[36:37], off
	v_add_co_u32_e32 v36, vcc, s44, v154
	s_nop 1
	v_addc_co_u32_e32 v37, vcc, 0, v155, vcc
	global_load_dwordx4 v[40:43], v[36:37], off
	v_add_co_u32_e32 v36, vcc, s2, v154
	s_nop 1
	v_addc_co_u32_e32 v37, vcc, 0, v155, vcc
	global_load_dwordx4 v[36:39], v[36:37], off
	s_waitcnt lgkmcnt(0)
	ds_read_b128 v[100:103], v176
	s_waitcnt vmcnt(23) lgkmcnt(0)
	v_pk_add_f32 v[96:97], v[96:97], v[100:101]
	v_add_co_u32_e32 v100, vcc, s20, v152
	v_pk_add_f32 v[98:99], v[98:99], v[102:103]
	s_nop 0
	v_addc_co_u32_e32 v101, vcc, 0, v153, vcc
	global_store_dwordx4 v[100:101], v[96:99], off
	ds_read_b128 v[96:99], v176 offset:1088
	s_waitcnt vmcnt(23) lgkmcnt(0)
	v_pk_add_f32 v[92:93], v[92:93], v[96:97]
	v_add_co_u32_e32 v96, vcc, s21, v152
	v_pk_add_f32 v[94:95], v[94:95], v[98:99]
	s_nop 0
	v_addc_co_u32_e32 v97, vcc, 0, v153, vcc
	global_store_dwordx4 v[96:97], v[92:95], off
	ds_read_b128 v[92:95], v176 offset:2176
	s_waitcnt vmcnt(23) lgkmcnt(0)
	v_pk_add_f32 v[88:89], v[88:89], v[92:93]
	v_add_co_u32_e32 v92, vcc, s30, v152
	v_pk_add_f32 v[90:91], v[90:91], v[94:95]
	s_nop 0
	v_addc_co_u32_e32 v93, vcc, 0, v153, vcc
	global_store_dwordx4 v[92:93], v[88:91], off
	ds_read_b128 v[88:91], v176 offset:3264
	s_waitcnt vmcnt(23) lgkmcnt(0)
	v_pk_add_f32 v[84:85], v[84:85], v[88:89]
	v_add_co_u32_e32 v88, vcc, s31, v152
	v_pk_add_f32 v[86:87], v[86:87], v[90:91]
	s_nop 0
	v_addc_co_u32_e32 v89, vcc, 0, v153, vcc
	global_store_dwordx4 v[88:89], v[84:87], off
	ds_read_b128 v[84:87], v176 offset:4352
	s_waitcnt vmcnt(23) lgkmcnt(0)
	v_pk_add_f32 v[80:81], v[80:81], v[84:85]
	v_add_co_u32_e32 v84, vcc, s58, v152
	v_pk_add_f32 v[82:83], v[82:83], v[86:87]
	s_nop 0
	v_addc_co_u32_e32 v85, vcc, 0, v153, vcc
	global_store_dwordx4 v[84:85], v[80:83], off
	ds_read_b128 v[80:83], v176 offset:5440
	s_waitcnt vmcnt(23) lgkmcnt(0)
	v_pk_add_f32 v[76:77], v[76:77], v[80:81]
	v_add_co_u32_e32 v80, vcc, s3, v152
	v_pk_add_f32 v[78:79], v[78:79], v[82:83]
	s_nop 0
	v_addc_co_u32_e32 v81, vcc, 0, v153, vcc
	global_store_dwordx4 v[80:81], v[76:79], off
	ds_read_b128 v[76:79], v176 offset:6528
	s_waitcnt vmcnt(23) lgkmcnt(0)
	v_pk_add_f32 v[72:73], v[72:73], v[76:77]
	v_add_co_u32_e32 v76, vcc, s59, v152
	v_pk_add_f32 v[74:75], v[74:75], v[78:79]
	s_nop 0
	v_addc_co_u32_e32 v77, vcc, 0, v153, vcc
	global_store_dwordx4 v[76:77], v[72:75], off
	ds_read_b128 v[72:75], v176 offset:7616
	s_waitcnt vmcnt(23) lgkmcnt(0)
	v_pk_add_f32 v[68:69], v[68:69], v[72:73]
	v_add_co_u32_e32 v72, vcc, s60, v152
	v_pk_add_f32 v[70:71], v[70:71], v[74:75]
	s_nop 0
	v_addc_co_u32_e32 v73, vcc, 0, v153, vcc
	global_store_dwordx4 v[72:73], v[68:71], off
	s_waitcnt lgkmcnt(0)
	ds_write_b128 v216, v[4:7]
	ds_write_b128 v216, v[8:11] offset:64
	ds_write_b128 v216, v[12:15] offset:128
	ds_write_b128 v216, v[16:19] offset:192
	ds_write_b128 v216, v[20:23] offset:4352
	ds_write_b128 v216, v[24:27] offset:4416
	ds_write_b128 v216, v[28:31] offset:4480
	ds_write_b128 v216, v[32:35] offset:4544
	s_waitcnt lgkmcnt(0)
	ds_read_b128 v[4:7], v176
	v_add_co_u32_e32 v8, vcc, s38, v152
	s_waitcnt vmcnt(15) lgkmcnt(0)
	v_pk_add_f32 v[4:5], v[64:65], v[4:5]
	v_pk_add_f32 v[6:7], v[66:67], v[6:7]
	v_addc_co_u32_e32 v9, vcc, 0, v153, vcc
	global_store_dwordx4 v[8:9], v[4:7], off
	ds_read_b128 v[4:7], v176 offset:1088
	v_add_co_u32_e32 v8, vcc, s39, v152
	s_waitcnt vmcnt(15) lgkmcnt(0)
	v_pk_add_f32 v[4:5], v[60:61], v[4:5]
	v_pk_add_f32 v[6:7], v[62:63], v[6:7]
	v_addc_co_u32_e32 v9, vcc, 0, v153, vcc
	global_store_dwordx4 v[8:9], v[4:7], off
	ds_read_b128 v[4:7], v176 offset:2176
	v_add_co_u32_e32 v8, vcc, s40, v152
	s_waitcnt vmcnt(15) lgkmcnt(0)
	v_pk_add_f32 v[4:5], v[56:57], v[4:5]
	v_pk_add_f32 v[6:7], v[58:59], v[6:7]
	v_addc_co_u32_e32 v9, vcc, 0, v153, vcc
	global_store_dwordx4 v[8:9], v[4:7], off
	ds_read_b128 v[4:7], v176 offset:3264
	v_add_co_u32_e32 v8, vcc, s41, v152
	s_waitcnt vmcnt(15) lgkmcnt(0)
	v_pk_add_f32 v[4:5], v[52:53], v[4:5]
	v_pk_add_f32 v[6:7], v[54:55], v[6:7]
	v_addc_co_u32_e32 v9, vcc, 0, v153, vcc
	global_store_dwordx4 v[8:9], v[4:7], off
	ds_read_b128 v[4:7], v176 offset:4352
	v_add_co_u32_e32 v8, vcc, s42, v152
	s_waitcnt vmcnt(15) lgkmcnt(0)
	v_pk_add_f32 v[4:5], v[48:49], v[4:5]
	v_pk_add_f32 v[6:7], v[50:51], v[6:7]
	v_addc_co_u32_e32 v9, vcc, 0, v153, vcc
	global_store_dwordx4 v[8:9], v[4:7], off
	ds_read_b128 v[4:7], v176 offset:5440
	v_add_co_u32_e32 v8, vcc, s43, v152
	s_waitcnt vmcnt(15) lgkmcnt(0)
	v_pk_add_f32 v[4:5], v[44:45], v[4:5]
	v_pk_add_f32 v[6:7], v[46:47], v[6:7]
	v_addc_co_u32_e32 v9, vcc, 0, v153, vcc
	global_store_dwordx4 v[8:9], v[4:7], off
	ds_read_b128 v[4:7], v176 offset:6528
	v_add_co_u32_e32 v8, vcc, s44, v152
	s_waitcnt vmcnt(15) lgkmcnt(0)
	v_pk_add_f32 v[4:5], v[40:41], v[4:5]
	v_pk_add_f32 v[6:7], v[42:43], v[6:7]
	v_addc_co_u32_e32 v9, vcc, 0, v153, vcc
	global_store_dwordx4 v[8:9], v[4:7], off
	ds_read_b128 v[4:7], v176 offset:7616
	v_add_co_u32_e32 v8, vcc, 0x7c000, v152
	s_waitcnt vmcnt(15) lgkmcnt(0)
	v_pk_add_f32 v[4:5], v[36:37], v[4:5]
	v_pk_add_f32 v[6:7], v[38:39], v[6:7]
	v_addc_co_u32_e32 v9, vcc, 0, v153, vcc
	global_store_dwordx4 v[8:9], v[4:7], off
	s_barrier
	s_cbranch_scc0 .LBB0_257
